# coalesced epilogue stores: 128B-wide LDS-transposed f32 residual stores with delayed issue, bpermute-coalesced bf16 AX and Mlp1 H stores
# speedup vs baseline: 1.0305x; 1.0029x over previous
; #define LAS __attribute__((address_space(3)))
;     __device__ __forceinline__ void operator()(const f32x4 (&acc)[2][2][4][2], const Unit& u, int wr, int wc, int fr, int fq) const {
;         const int b = u.pm >> 3, col0 = u.pn * 256 + wc * 32 + 8 * fq;
;         { const int t = (wr * 4 + wc) * 64 + fq * 16 + fr;
;           if (t < 64) ((LAS f32x4*)gl)[t] = *(const f32x4*)(gate + (size_t)b * gate_ld + u.pn * 256 + 4 * t);
;           else if (t < 128 && gmn) ((LAS f32x4*)gl)[t] = *(const f32x4*)(gmn + (size_t)b * DM + u.pn * 256 + 4 * (t - 64));
;           asm volatile("s_waitcnt vmcnt(0) lgkmcnt(0)" ::: "memory"); __builtin_amdgcn_s_barrier(); asm volatile("" ::: "memory"); }
;         const LAS float* gtp = gl + wc * 32 + 8 * fq; const LAS float* gmp = gl + 256 + wc * 32 + 8 * fq;
.LBB0_212:
	s_mul_i32 s100, s5, 36
	s_add_i32 s100, s100, 0x24000
	s_cmp_eq_u32 s5, 0x1c0
	s_cselect_b32 s100, 0x20c00, s100
	s_lshl_b32 s101, s5, 4
	s_add_i32 s101, s101, 0x21800
	v_lshrrev_b32_e32 v210, 3, v242
	v_and_b32_e32 v246, 7, v242
	v_mul_u32_u24_e32 v210, 0x90, v210
	v_lshl_add_u32 v210, v246, 4, v210
	v_add_u32_e32 v210, s100, v210
	v_mul_u32_u24_e32 v208, 0x90, v211
	v_lshl_add_u32 v208, v207, 5, v208
	v_add_u32_e32 v208, s100, v208
	v_lshrrev_b32_e32 v252, 3, v242
	v_sub_u32_e32 v252, v252, v211
	v_lshlrev_b32_e32 v252, 12, v252
	v_lshl_add_u32 v246, v246, 4, v252
	v_lshlrev_b32_e32 v252, 5, v207
	v_sub_u32_e32 v246, v246, v252
	v_lshl_add_u32 v252, v242, 2, s101
	ds_write_b32 v252, v216
	ds_write_b32 v252, v218 offset:256
	ds_write_b32 v252, v220 offset:512
	ds_write_b32 v252, v222 offset:768
	s_add_u32 s100, s20, 0x8000
	s_addc_u32 s101, s21, 0
	v_and_b32_e32 v206, 3, v242
	v_lshrrev_b32_e32 v204, 2, v242
	v_lshl_add_u32 v205, v206, 4, v204
	v_sub_u32_e32 v204, v204, v211
	v_sub_u32_e32 v206, v206, v207
	v_lshlrev_b32_e32 v204, 11, v204
	v_lshl_add_u32 v204, v206, 4, v204
	v_lshlrev_b32_e32 v206, 2, v205
	v_ashrrev_i32_e32 v205, 31, v204
	v_mov_b32_e32 v106, v211
	v_mov_b32_e32 v250, v207
	s_ashr_i32 s46, s77, 3
	v_lshlrev_b32_e32 v104, 4, v250
	v_add3_u32 v107, s5, v106, v104
	s_lshl_b32 s44, s76, 8
	v_cmp_lt_i32_e32 vcc, 63, v107
	s_mov_b64 s[56:57], 0
	s_and_saveexec_b64 s[54:55], vcc
	s_xor_b64 s[54:55], exec, s[54:55]
	s_movk_i32 s63, 0x5ff
	s_cbranch_execnz .LBB0_261
	s_andn2_saveexec_b64 s[54:55], s[54:55]
	s_cbranch_execnz .LBB0_264

; #define LAS __attribute__((address_space(3)))
; __device__ __forceinline__ unsigned cvt_pk_bf16(float lo, float hi) { const cvt_f32x2_t v = {lo, hi}; const cvt_bf16x2_t b = __builtin_convertvector(v, cvt_bf16x2_t); return __builtin_bit_cast(unsigned, b); }
; __device__ __forceinline__ float sq4(f32x4 v) { return (v[0] * v[0] + v[1] * v[1]) + (v[2] * v[2] + v[3] * v[3]); }
;     __device__ __forceinline__ void operator()(const f32x4 (&acc)[2][2][4][2], const Unit& u, int wr, int wc, int fr, int fq) const {
;     ...
; #pragma unroll
;         for (int ai = 0; ai < 2; ++ai) {
;             f32x4 xr[4][2][2];
; #pragma unroll
;             for (int m = 0; m < 4; ++m) { const size_t off = (size_t)(u.pm * 256 + ai * 128 + wr * 64 + m * 16 + fr) * DM + col0;
; #pragma unroll
;                 for (int bj = 0; bj < 2; ++bj)
; #pragma unroll
;                     for (int n = 0; n < 2; ++n) xr[m][bj][n] = *(const f32x4*)(xin + off + 128 * bj + 4 * n); }
;             asm volatile("" ::: "memory");
; #pragma unroll
;             for (int m = 0; m < 4; ++m) {
;                 const int row = u.pm * 256 + ai * 128 + wr * 64 + m * 16 + fr;
;                 const size_t off = (size_t)row * DM + col0;
;                 float ss = 0.f;
; #pragma unroll
;                 for (int bj = 0; bj < 2; ++bj) {
;                     const f32x4 xo0 = xr[m][bj][0] + *(const LAS f32x4*)(gtp + 128 * bj) * acc[ai][bj][m][0], xo1 = xr[m][bj][1] + *(const LAS f32x4*)(gtp + 128 * bj + 4) * acc[ai][bj][m][1];
;                     *(f32x4*)(xout + off + 128 * bj) = xo0; *(f32x4*)(xout + off + 128 * bj + 4) = xo1;
;                     if (gmn) { ss += sq4(xo0) + sq4(xo1); const f32x4 a = xo0 * *(const LAS f32x4*)(gmp + 128 * bj), c = xo1 * *(const LAS f32x4*)(gmp + 128 * bj + 4);
;                         u32x4 w; w.x = cvt_pk_bf16(a[0], a[1]); w.y = cvt_pk_bf16(a[2], a[3]); w.z = cvt_pk_bf16(c[0], c[1]); w.w = cvt_pk_bf16(c[2], c[3]); *(u32x4*)(AX + off + 128 * bj) = w; }
;                 }
;                 if (gmn) { ss += __shfl_xor(ss, 16); ss += __shfl_xor(ss, 32); if (fq == 0) statx[(size_t)row * 16 + u.pn * 4 + wc] = ss; }
.LBB0_216:
	s_or_b64 exec, exec, s[46:47]
	s_or_b32 s44, s44, s58
	v_lshl_add_u32 v224, v250, 3, s44
	s_lshl_b32 s44, s77, 8
	s_add_i32 s44, s44, s7
	v_add_u32_e32 v226, s44, v106
	v_readlane_b32 s44, v255, 46
	v_lshlrev_b32_e32 v104, 5, v250
	v_ashrrev_i32_e32 v225, 31, v224
	v_readlane_b32 s45, v255, 47
	v_ashrrev_i32_e32 v227, 31, v226
	v_add_u32_e32 v249, s87, v104
	v_add_u32_e32 v192, s8, v104
	v_lshl_add_u64 v[228:229], v[224:225], 2, s[44:45]
	v_lshlrev_b64 v[104:105], 12, v[226:227]
	v_add_u32_e32 v234, 16, v226
	s_waitcnt vmcnt(0) lgkmcnt(0)
	s_barrier
	v_lshl_add_u64 v[104:105], v[228:229], 0, v[104:105]
	v_ashrrev_i32_e32 v235, 31, v234
	global_load_dwordx4 v[194:197], v[104:105], off offset:16
	global_load_dwordx4 v[198:201], v[104:105], off
	global_load_dwordx4 v[184:187], v[104:105], off offset:528
	global_load_dwordx4 v[188:191], v[104:105], off offset:512
	v_lshlrev_b64 v[104:105], 12, v[234:235]
	v_add_u32_e32 v232, 32, v226
	v_lshl_add_u64 v[104:105], v[228:229], 0, v[104:105]
	v_ashrrev_i32_e32 v233, 31, v232
	global_load_dwordx4 v[176:179], v[104:105], off offset:16
	global_load_dwordx4 v[180:183], v[104:105], off
	global_load_dwordx4 v[168:171], v[104:105], off offset:528
	global_load_dwordx4 v[172:175], v[104:105], off offset:512
	v_lshlrev_b64 v[104:105], 12, v[232:233]
	v_add_u32_e32 v230, 48, v226
	v_lshl_add_u64 v[104:105], v[228:229], 0, v[104:105]
	v_ashrrev_i32_e32 v231, 31, v230
	global_load_dwordx4 v[160:163], v[104:105], off offset:16
	global_load_dwordx4 v[164:167], v[104:105], off
	global_load_dwordx4 v[152:155], v[104:105], off offset:528
	global_load_dwordx4 v[156:159], v[104:105], off offset:512
	v_lshlrev_b64 v[104:105], 12, v[230:231]
	v_lshl_add_u64 v[112:113], v[228:229], 0, v[104:105]
	global_load_dwordx4 v[136:139], v[112:113], off offset:16
	global_load_dwordx4 v[144:147], v[112:113], off
	global_load_dwordx4 v[104:107], v[112:113], off offset:528
	s_nop 0
	global_load_dwordx4 v[112:115], v[112:113], off offset:512
	v_lshlrev_b64 v[140:141], 10, v[226:227]
	v_lshl_add_u64 v[202:203], v[140:141], 0, v[224:225]
	ds_read_b128 v[148:151], v249
	ds_read_b128 v[140:143], v249 offset:16
	v_lshl_add_u64 v[236:237], v[202:203], 2, s[20:21]
	v_lshl_add_u32 v236, v202, 2, v246
	v_mov_b32_e32 v251, 0
	s_andn2_b64 vcc, exec, s[40:41]
	v_lshl_add_u64 v[238:239], v[202:203], 1, s[16:17]
	v_lshl_add_u64 v[238:239], v[204:205], 0, v[238:239]
	s_waitcnt vmcnt(0) lgkmcnt(0)
	v_pk_fma_f32 v[128:129], v[128:129], v[140:141], v[194:195]
	v_cndmask_b32_e64 v194, 0, 1, s[40:41]
	v_pk_fma_f32 v[134:135], v[134:135], v[150:151], v[200:201]
	v_pk_fma_f32 v[132:133], v[132:133], v[148:149], v[198:199]
	v_pk_fma_f32 v[130:131], v[130:131], v[142:143], v[196:197]
	v_cmp_ne_u32_e64 s[46:47], 1, v194
	ds_write_b128 v208, v[132:135]
	ds_write_b128 v208, v[128:131] offset:16
	ds_read_b128 v[216:219], v210
	ds_read_b128 v[220:223], v210 offset:1152
	s_waitcnt lgkmcnt(0)
	global_store_dwordx4 v236, v[216:219], s[20:21]
	global_store_dwordx4 v236, v[220:223], s[100:101]
	s_cbranch_vccnz .LBB0_218
	v_mov_b32_e32 v196, v133
	v_mov_b32_e32 v197, v129
	v_mov_b32_e32 v194, v132
	v_mov_b32_e32 v195, v128
	v_pk_mul_f32 v[196:197], v[196:197], v[196:197]
	v_mov_b32_e32 v198, v135
	v_mov_b32_e32 v199, v131
	v_pk_fma_f32 v[194:195], v[194:195], v[194:195], v[196:197]
	v_mov_b32_e32 v196, v134
	v_mov_b32_e32 v197, v130
	v_pk_mul_f32 v[198:199], v[198:199], v[198:199]
	s_nop 0
	v_pk_fma_f32 v[196:197], v[196:197], v[196:197], v[198:199]
	s_nop 0
	v_pk_add_f32 v[194:195], v[194:195], v[196:197]
	s_nop 0
	v_add_f32_e32 v251, v194, v195
	ds_read_b128 v[194:197], v192
	ds_read_b128 v[198:201], v192 offset:16
	s_waitcnt lgkmcnt(1)
	v_pk_mul_f32 v[134:135], v[134:135], v[196:197]
	v_pk_mul_f32 v[132:133], v[132:133], v[194:195]
	s_waitcnt lgkmcnt(0)
	v_pk_mul_f32 v[194:195], v[130:131], v[200:201]
	v_pk_mul_f32 v[130:131], v[128:129], v[198:199]
	v_cvt_pk_bf16_f32 v128, v132, v133
	v_cvt_pk_bf16_f32 v129, v134, v135
	v_cvt_pk_bf16_f32 v130, v130, v131
	v_cvt_pk_bf16_f32 v131, v194, v195
	ds_bpermute_b32 v128, v206, v128
	ds_bpermute_b32 v129, v206, v129
	ds_bpermute_b32 v130, v206, v130
	ds_bpermute_b32 v131, v206, v131
	s_waitcnt lgkmcnt(0)
	global_store_dwordx4 v[238:239], v[128:131], off
.LBB0_218:
	ds_read_b128 v[132:135], v249 offset:512
	ds_read_b128 v[128:131], v249 offset:528
	s_lshl_b32 s76, s76, 2
	v_cmp_eq_u32_e64 s[44:45], 0, v250
	s_ashr_i32 s77, s76, 31
	s_waitcnt lgkmcnt(1)
	v_pk_fma_f32 v[126:127], v[126:127], v[134:135], v[190:191]
	v_pk_fma_f32 v[124:125], v[124:125], v[132:133], v[188:189]
	s_waitcnt lgkmcnt(0)
	v_pk_fma_f32 v[122:123], v[122:123], v[130:131], v[186:187]
	v_pk_fma_f32 v[120:121], v[120:121], v[128:129], v[184:185]
	s_and_b64 vcc, exec, s[46:47]
	ds_write_b128 v208, v[124:127]
	ds_write_b128 v208, v[120:123] offset:16
	ds_read_b128 v[216:219], v210
	ds_read_b128 v[220:223], v210 offset:1152
	s_waitcnt lgkmcnt(0)
	global_store_dwordx4 v236, v[216:219], s[20:21] offset:512
	global_store_dwordx4 v236, v[220:223], s[100:101] offset:512
	s_cbranch_vccnz .LBB0_222
	ds_read_b128 v[184:187], v192 offset:512
	ds_read_b128 v[188:191], v192 offset:528
	s_waitcnt lgkmcnt(1)
	v_pk_mul_f32 v[184:185], v[124:125], v[184:185]
	s_waitcnt lgkmcnt(0)
	v_pk_mul_f32 v[188:189], v[120:121], v[188:189]
	v_mul_f32_e32 v121, v121, v121
	v_mul_f32_e32 v125, v125, v125
	v_fmac_f32_e32 v121, v120, v120
	v_mul_f32_e32 v120, v123, v123
	v_pk_mul_f32 v[190:191], v[122:123], v[190:191]
	v_fmac_f32_e32 v125, v124, v124
	v_mul_f32_e32 v124, v127, v127
	v_fmac_f32_e32 v120, v122, v122
	v_and_b32_e32 v122, 64, v242
	v_fmac_f32_e32 v124, v126, v126
	v_add_f32_e32 v120, v121, v120
	v_xor_b32_e32 v121, 16, v242
	v_add_u32_e32 v122, 64, v122
	v_add_f32_e32 v124, v125, v124
	v_cmp_lt_i32_e32 vcc, v121, v122
	v_add_f32_e32 v120, v124, v120
	v_add_f32_e32 v120, v251, v120
	v_cndmask_b32_e32 v121, v242, v121, vcc
	v_lshlrev_b32_e32 v121, 2, v121
	ds_bpermute_b32 v121, v121, v120
	v_pk_mul_f32 v[186:187], v[126:127], v[186:187]
	v_cvt_pk_bf16_f32 v184, v184, v185
	v_cvt_pk_bf16_f32 v185, v186, v187
	v_cvt_pk_bf16_f32 v186, v188, v189
	s_waitcnt lgkmcnt(0)
	v_add_f32_e32 v120, v120, v121
	v_xor_b32_e32 v121, 32, v242
	v_cmp_lt_i32_e32 vcc, v121, v122
	v_cvt_pk_bf16_f32 v187, v190, v191
	ds_bpermute_b32 v184, v206, v184
	ds_bpermute_b32 v185, v206, v185
	ds_bpermute_b32 v186, v206, v186
	ds_bpermute_b32 v187, v206, v187
	s_waitcnt lgkmcnt(0)
	global_store_dwordx4 v[238:239], v[184:187], off offset:256
	v_cndmask_b32_e32 v121, v242, v121, vcc
	v_lshlrev_b32_e32 v121, 2, v121
	ds_bpermute_b32 v121, v121, v120
	s_and_saveexec_b64 s[54:55], s[44:45]
	s_cbranch_execz .LBB0_221
	v_lshlrev_b64 v[122:123], 6, v[226:227]
	v_lshl_add_u64 v[122:123], s[22:23], 0, v[122:123]
	v_lshl_add_u64 v[122:123], s[76:77], 2, v[122:123]
	s_lshl_b32 s92, s6, 2
	v_lshl_add_u64 v[122:123], v[122:123], 0, s[92:93]
	s_waitcnt lgkmcnt(0)
	v_add_f32_e32 v120, v120, v121
	global_store_dword v[122:123], v120, off

; #define LAS __attribute__((address_space(3)))
; __device__ __forceinline__ unsigned cvt_pk_bf16(float lo, float hi) { const cvt_f32x2_t v = {lo, hi}; const cvt_bf16x2_t b = __builtin_convertvector(v, cvt_bf16x2_t); return __builtin_bit_cast(unsigned, b); }
; __device__ __forceinline__ float sq4(f32x4 v) { return (v[0] * v[0] + v[1] * v[1]) + (v[2] * v[2] + v[3] * v[3]); }
;     __device__ __forceinline__ void operator()(const f32x4 (&acc)[2][2][4][2], const Unit& u, int wr, int wc, int fr, int fq) const {
;     ...
;             for (int m = 0; m < 4; ++m) {
;                 const int row = u.pm * 256 + ai * 128 + wr * 64 + m * 16 + fr;
;                 const size_t off = (size_t)row * DM + col0;
;                 float ss = 0.f;
; #pragma unroll
;                 for (int bj = 0; bj < 2; ++bj) {
;                     const f32x4 xo0 = xr[m][bj][0] + *(const LAS f32x4*)(gtp + 128 * bj) * acc[ai][bj][m][0], xo1 = xr[m][bj][1] + *(const LAS f32x4*)(gtp + 128 * bj + 4) * acc[ai][bj][m][1];
;                     *(f32x4*)(xout + off + 128 * bj) = xo0; *(f32x4*)(xout + off + 128 * bj + 4) = xo1;
;                     if (gmn) { ss += sq4(xo0) + sq4(xo1); const f32x4 a = xo0 * *(const LAS f32x4*)(gmp + 128 * bj), c = xo1 * *(const LAS f32x4*)(gmp + 128 * bj + 4);
;                         u32x4 w; w.x = cvt_pk_bf16(a[0], a[1]); w.y = cvt_pk_bf16(a[2], a[3]); w.z = cvt_pk_bf16(c[0], c[1]); w.w = cvt_pk_bf16(c[2], c[3]); *(u32x4*)(AX + off + 128 * bj) = w; }
;                 }
;                 if (gmn) { ss += __shfl_xor(ss, 16); ss += __shfl_xor(ss, 32); if (fq == 0) statx[(size_t)row * 16 + u.pn * 4 + wc] = ss; }
.LBB0_222:
	s_waitcnt lgkmcnt(0)
	v_lshlrev_b64 v[120:121], 10, v[234:235]
	v_lshl_add_u64 v[184:185], v[120:121], 0, v[224:225]
	v_pk_fma_f32 v[120:121], v[118:119], v[150:151], v[182:183]
	v_pk_fma_f32 v[118:119], v[116:117], v[148:149], v[180:181]
	v_pk_fma_f32 v[124:125], v[110:111], v[142:143], v[178:179]
	v_pk_fma_f32 v[122:123], v[108:109], v[140:141], v[176:177]
	v_lshl_add_u64 v[126:127], v[184:185], 2, s[20:21]
	v_lshl_add_u32 v126, v184, 2, v246
	s_mov_b64 s[54:55], -1
	s_and_b64 vcc, exec, s[46:47]
	v_pk_fma_f32 v[116:117], v[100:101], v[132:133], v[172:173]
	v_pk_fma_f32 v[108:109], v[92:93], v[128:129], v[168:169]
	ds_write_b128 v208, v[118:121]
	ds_write_b128 v208, v[122:125] offset:16
	ds_read_b128 v[216:219], v210
	ds_read_b128 v[220:223], v210 offset:1152
	s_waitcnt lgkmcnt(0)
	global_store_dwordx4 v126, v[216:219], s[20:21]
	global_store_dwordx4 v126, v[220:223], s[100:101]
	s_cbranch_vccnz .LBB0_226
	v_mul_f32_e32 v92, v119, v119
	v_mul_f32_e32 v93, v121, v121
	ds_read_b128 v[176:179], v192
	ds_read_b128 v[180:183], v192 offset:16
	v_fmac_f32_e32 v92, v118, v118
	v_fmac_f32_e32 v93, v120, v120
	v_add_f32_e32 v92, v92, v93
	v_mul_f32_e32 v93, v123, v123
	v_mul_f32_e32 v100, v125, v125
	v_fmac_f32_e32 v93, v122, v122
	v_fmac_f32_e32 v100, v124, v124
	v_add_f32_e32 v93, v93, v100
	v_add_f32_e32 v172, v92, v93
	s_waitcnt lgkmcnt(1)
	v_pk_mul_f32 v[92:93], v[120:121], v[178:179]
	v_pk_mul_f32 v[100:101], v[118:119], v[176:177]
	s_waitcnt lgkmcnt(0)
	v_pk_mul_f32 v[110:111], v[124:125], v[182:183]
	v_pk_mul_f32 v[120:121], v[122:123], v[180:181]
	v_cvt_pk_bf16_f32 v118, v100, v101
	v_cvt_pk_bf16_f32 v119, v92, v93
	v_cvt_pk_bf16_f32 v120, v120, v121
	v_cvt_pk_bf16_f32 v121, v110, v111
	v_lshl_add_u64 v[92:93], v[184:185], 1, s[16:17]
	ds_bpermute_b32 v118, v206, v118
	ds_bpermute_b32 v119, v206, v119
	ds_bpermute_b32 v120, v206, v120
	ds_bpermute_b32 v121, v206, v121
	s_waitcnt lgkmcnt(0)
	v_lshl_add_u64 v[92:93], v[204:205], 0, v[92:93]
	global_store_dwordx4 v[92:93], v[118:121], off
	v_pk_fma_f32 v[110:111], v[94:95], v[130:131], v[170:171]
	s_nop 0
	v_pk_fma_f32 v[118:119], v[102:103], v[134:135], v[174:175]
	ds_write_b128 v208, v[116:119]
	ds_write_b128 v208, v[108:111] offset:16
	ds_read_b128 v[216:219], v210
	ds_read_b128 v[220:223], v210 offset:1152
	ds_read_b128 v[120:123], v192 offset:512
	s_waitcnt lgkmcnt(0)
	v_pk_mul_f32 v[100:101], v[118:119], v[122:123]
	v_pk_mul_f32 v[124:125], v[116:117], v[120:121]
	ds_read_b128 v[120:123], v192 offset:528
	s_waitcnt lgkmcnt(0)
	v_pk_mul_f32 v[168:169], v[110:111], v[122:123]
	v_pk_mul_f32 v[122:123], v[108:109], v[120:121]
	v_cvt_pk_bf16_f32 v120, v124, v125
	v_cvt_pk_bf16_f32 v121, v100, v101
	s_waitcnt lgkmcnt(0)
	global_store_dwordx4 v126, v[216:219], s[20:21] offset:512
	global_store_dwordx4 v126, v[220:223], s[100:101] offset:512
	v_cvt_pk_bf16_f32 v122, v122, v123
	v_cvt_pk_bf16_f32 v123, v168, v169
	ds_bpermute_b32 v120, v206, v120
	ds_bpermute_b32 v121, v206, v121
	ds_bpermute_b32 v122, v206, v122
	ds_bpermute_b32 v123, v206, v123
	s_waitcnt lgkmcnt(0)
	global_store_dwordx4 v[92:93], v[120:123], off offset:256
	v_mul_f32_e32 v92, v117, v117
	v_mul_f32_e32 v93, v119, v119
	v_fmac_f32_e32 v92, v116, v116
	v_fmac_f32_e32 v93, v118, v118
	v_add_f32_e32 v92, v92, v93
	v_mul_f32_e32 v93, v109, v109
	v_mul_f32_e32 v100, v111, v111
	v_fmac_f32_e32 v93, v108, v108
	v_fmac_f32_e32 v100, v110, v110
	v_add_f32_e32 v93, v93, v100
	v_and_b32_e32 v100, 64, v242
	v_add_f32_e32 v92, v92, v93
	v_xor_b32_e32 v93, 16, v242
	v_add_u32_e32 v100, 64, v100
	v_cmp_lt_i32_e32 vcc, v93, v100
	v_add_f32_e32 v92, v172, v92
	s_nop 0
	v_cndmask_b32_e32 v93, v242, v93, vcc
	v_lshlrev_b32_e32 v93, 2, v93
	ds_bpermute_b32 v93, v93, v92
	s_waitcnt lgkmcnt(0)
	v_add_f32_e32 v92, v92, v93
	v_xor_b32_e32 v93, 32, v242
	v_cmp_lt_i32_e32 vcc, v93, v100
	s_nop 1
	v_cndmask_b32_e32 v93, v242, v93, vcc
	v_lshlrev_b32_e32 v93, 2, v93
	ds_bpermute_b32 v93, v93, v92
	s_and_saveexec_b64 s[54:55], s[44:45]
	s_cbranch_execz .LBB0_225
	v_lshlrev_b64 v[100:101], 6, v[234:235]
	v_lshl_add_u64 v[100:101], s[22:23], 0, v[100:101]
	v_lshl_add_u64 v[100:101], s[76:77], 2, v[100:101]
	s_lshl_b32 s92, s6, 2
	v_lshl_add_u64 v[100:101], v[100:101], 0, s[92:93]
	s_waitcnt lgkmcnt(0)
	v_add_f32_e32 v92, v92, v93
	global_store_dword v[100:101], v92, off

; #define LAS __attribute__((address_space(3)))
; __device__ __forceinline__ unsigned cvt_pk_bf16(float lo, float hi) { const cvt_f32x2_t v = {lo, hi}; const cvt_bf16x2_t b = __builtin_convertvector(v, cvt_bf16x2_t); return __builtin_bit_cast(unsigned, b); }
; __device__ __forceinline__ float sq4(f32x4 v) { return (v[0] * v[0] + v[1] * v[1]) + (v[2] * v[2] + v[3] * v[3]); }
;     __device__ __forceinline__ void operator()(const f32x4 (&acc)[2][2][4][2], const Unit& u, int wr, int wc, int fr, int fq) const {
;     ...
;             for (int m = 0; m < 4; ++m) {
;                 const int row = u.pm * 256 + ai * 128 + wr * 64 + m * 16 + fr;
;                 const size_t off = (size_t)row * DM + col0;
;                 float ss = 0.f;
; #pragma unroll
;                 for (int bj = 0; bj < 2; ++bj) {
;                     const f32x4 xo0 = xr[m][bj][0] + *(const LAS f32x4*)(gtp + 128 * bj) * acc[ai][bj][m][0], xo1 = xr[m][bj][1] + *(const LAS f32x4*)(gtp + 128 * bj + 4) * acc[ai][bj][m][1];
;                     *(f32x4*)(xout + off + 128 * bj) = xo0; *(f32x4*)(xout + off + 128 * bj + 4) = xo1;
;                     if (gmn) { ss += sq4(xo0) + sq4(xo1); const f32x4 a = xo0 * *(const LAS f32x4*)(gmp + 128 * bj), c = xo1 * *(const LAS f32x4*)(gmp + 128 * bj + 4);
;                         u32x4 w; w.x = cvt_pk_bf16(a[0], a[1]); w.y = cvt_pk_bf16(a[2], a[3]); w.z = cvt_pk_bf16(c[0], c[1]); w.w = cvt_pk_bf16(c[2], c[3]); *(u32x4*)(AX + off + 128 * bj) = w; }
;                 }
;                 if (gmn) { ss += __shfl_xor(ss, 16); ss += __shfl_xor(ss, 32); if (fq == 0) statx[(size_t)row * 16 + u.pn * 4 + wc] = ss; }
.LBB0_226:
	s_andn2_b64 vcc, exec, s[54:55]
	s_cbranch_vccnz .LBB0_228
	v_pk_fma_f32 v[118:119], v[102:103], v[134:135], v[174:175]
	v_pk_fma_f32 v[110:111], v[94:95], v[130:131], v[170:171]
	ds_write_b128 v208, v[116:119]
	ds_write_b128 v208, v[108:111] offset:16
	ds_read_b128 v[216:219], v210
	ds_read_b128 v[220:223], v210 offset:1152
	s_waitcnt lgkmcnt(0)
	global_store_dwordx4 v126, v[216:219], s[20:21] offset:512
	global_store_dwordx4 v126, v[220:223], s[100:101] offset:512
.LBB0_228:
	s_waitcnt lgkmcnt(0)
	v_lshlrev_b64 v[92:93], 10, v[232:233]
	v_lshl_add_u64 v[94:95], v[92:93], 0, v[224:225]
	v_pk_fma_f32 v[98:99], v[98:99], v[150:151], v[166:167]
	v_pk_fma_f32 v[96:97], v[96:97], v[148:149], v[164:165]
	v_pk_fma_f32 v[102:103], v[90:91], v[142:143], v[162:163]
	v_pk_fma_f32 v[100:101], v[88:89], v[140:141], v[160:161]
	v_lshl_add_u64 v[108:109], v[94:95], 2, s[20:21]
	v_lshl_add_u32 v108, v94, 2, v246
	s_mov_b64 s[54:55], -1
	s_and_b64 vcc, exec, s[46:47]
	v_pk_fma_f32 v[92:93], v[84:85], v[132:133], v[156:157]
	v_pk_fma_f32 v[88:89], v[76:77], v[128:129], v[152:153]
	ds_write_b128 v208, v[96:99]
	ds_write_b128 v208, v[100:103] offset:16
	ds_read_b128 v[216:219], v210
	ds_read_b128 v[220:223], v210 offset:1152
	s_waitcnt lgkmcnt(0)
	global_store_dwordx4 v108, v[216:219], s[20:21]
	global_store_dwordx4 v108, v[220:223], s[100:101]
	s_cbranch_vccnz .LBB0_232
	v_mul_f32_e32 v76, v97, v97
	v_mul_f32_e32 v77, v99, v99
	ds_read_b128 v[116:119], v192
	ds_read_b128 v[120:123], v192 offset:16
	v_fmac_f32_e32 v76, v96, v96
	v_fmac_f32_e32 v77, v98, v98
	v_add_f32_e32 v76, v76, v77
	v_mul_f32_e32 v77, v101, v101
	v_mul_f32_e32 v84, v103, v103
	v_fmac_f32_e32 v77, v100, v100
	v_fmac_f32_e32 v84, v102, v102
	v_add_f32_e32 v77, v77, v84
	v_add_f32_e32 v110, v76, v77
	s_waitcnt lgkmcnt(1)
	v_pk_mul_f32 v[76:77], v[98:99], v[118:119]
	v_pk_mul_f32 v[84:85], v[96:97], v[116:117]
	s_waitcnt lgkmcnt(0)
	v_pk_mul_f32 v[90:91], v[102:103], v[122:123]
	v_pk_mul_f32 v[98:99], v[100:101], v[120:121]
	v_cvt_pk_bf16_f32 v96, v84, v85
	v_cvt_pk_bf16_f32 v97, v76, v77
	v_cvt_pk_bf16_f32 v98, v98, v99
	v_cvt_pk_bf16_f32 v99, v90, v91
	v_lshl_add_u64 v[76:77], v[94:95], 1, s[16:17]
	v_lshl_add_u64 v[76:77], v[204:205], 0, v[76:77]
	v_pk_fma_f32 v[94:95], v[86:87], v[134:135], v[158:159]
	ds_bpermute_b32 v96, v206, v96
	ds_bpermute_b32 v97, v206, v97
	ds_bpermute_b32 v98, v206, v98
	ds_bpermute_b32 v99, v206, v99
	s_waitcnt lgkmcnt(0)
	global_store_dwordx4 v[76:77], v[96:99], off
	v_pk_fma_f32 v[90:91], v[78:79], v[130:131], v[154:155]
	ds_write_b128 v208, v[92:95]
	ds_write_b128 v208, v[88:91] offset:16
	ds_read_b128 v[216:219], v210
	ds_read_b128 v[220:223], v210 offset:1152
	ds_read_b128 v[96:99], v192 offset:512
	s_waitcnt lgkmcnt(0)
	v_pk_mul_f32 v[84:85], v[94:95], v[98:99]
	v_pk_mul_f32 v[100:101], v[92:93], v[96:97]
	ds_read_b128 v[96:99], v192 offset:528
	s_waitcnt lgkmcnt(0)
	v_pk_mul_f32 v[102:103], v[90:91], v[98:99]
	v_pk_mul_f32 v[98:99], v[88:89], v[96:97]
	v_cvt_pk_bf16_f32 v96, v100, v101
	v_cvt_pk_bf16_f32 v97, v84, v85
	s_waitcnt lgkmcnt(0)
	global_store_dwordx4 v108, v[216:219], s[20:21] offset:512
	global_store_dwordx4 v108, v[220:223], s[100:101] offset:512
	v_cvt_pk_bf16_f32 v98, v98, v99
	v_cvt_pk_bf16_f32 v99, v102, v103
	ds_bpermute_b32 v96, v206, v96
	ds_bpermute_b32 v97, v206, v97
	ds_bpermute_b32 v98, v206, v98
	ds_bpermute_b32 v99, v206, v99
	s_waitcnt lgkmcnt(0)
	global_store_dwordx4 v[76:77], v[96:99], off offset:256
	v_mul_f32_e32 v76, v93, v93
	v_mul_f32_e32 v77, v95, v95
	v_fmac_f32_e32 v76, v92, v92
	v_fmac_f32_e32 v77, v94, v94
	v_add_f32_e32 v76, v76, v77
	v_mul_f32_e32 v77, v89, v89
	v_mul_f32_e32 v84, v91, v91
	v_fmac_f32_e32 v77, v88, v88
	v_fmac_f32_e32 v84, v90, v90
	v_add_f32_e32 v77, v77, v84
	v_and_b32_e32 v84, 64, v242
	v_add_f32_e32 v76, v76, v77
	v_xor_b32_e32 v77, 16, v242
	v_add_u32_e32 v84, 64, v84
	v_cmp_lt_i32_e32 vcc, v77, v84
	v_add_f32_e32 v76, v110, v76
	s_nop 0
	v_cndmask_b32_e32 v77, v242, v77, vcc
	v_lshlrev_b32_e32 v77, 2, v77
	ds_bpermute_b32 v77, v77, v76
	s_waitcnt lgkmcnt(0)
	v_add_f32_e32 v76, v76, v77
	v_xor_b32_e32 v77, 32, v242
	v_cmp_lt_i32_e32 vcc, v77, v84
	s_nop 1
	v_cndmask_b32_e32 v77, v242, v77, vcc
	v_lshlrev_b32_e32 v77, 2, v77
	ds_bpermute_b32 v77, v77, v76
	s_and_saveexec_b64 s[54:55], s[44:45]
	s_cbranch_execz .LBB0_231
	v_lshlrev_b64 v[84:85], 6, v[232:233]
	v_lshl_add_u64 v[84:85], s[22:23], 0, v[84:85]
	v_lshl_add_u64 v[84:85], s[76:77], 2, v[84:85]
	s_lshl_b32 s92, s6, 2
	v_lshl_add_u64 v[84:85], v[84:85], 0, s[92:93]
	s_waitcnt lgkmcnt(0)
	v_add_f32_e32 v76, v76, v77
	global_store_dword v[84:85], v76, off

; #define LAS __attribute__((address_space(3)))
; __device__ __forceinline__ unsigned cvt_pk_bf16(float lo, float hi) { const cvt_f32x2_t v = {lo, hi}; const cvt_bf16x2_t b = __builtin_convertvector(v, cvt_bf16x2_t); return __builtin_bit_cast(unsigned, b); }
; __device__ __forceinline__ float sq4(f32x4 v) { return (v[0] * v[0] + v[1] * v[1]) + (v[2] * v[2] + v[3] * v[3]); }
;     __device__ __forceinline__ void operator()(const f32x4 (&acc)[2][2][4][2], const Unit& u, int wr, int wc, int fr, int fq) const {
;     ...
;             for (int m = 0; m < 4; ++m) {
;                 const int row = u.pm * 256 + ai * 128 + wr * 64 + m * 16 + fr;
;                 const size_t off = (size_t)row * DM + col0;
;                 float ss = 0.f;
; #pragma unroll
;                 for (int bj = 0; bj < 2; ++bj) {
;                     const f32x4 xo0 = xr[m][bj][0] + *(const LAS f32x4*)(gtp + 128 * bj) * acc[ai][bj][m][0], xo1 = xr[m][bj][1] + *(const LAS f32x4*)(gtp + 128 * bj + 4) * acc[ai][bj][m][1];
;                     *(f32x4*)(xout + off + 128 * bj) = xo0; *(f32x4*)(xout + off + 128 * bj + 4) = xo1;
;                     if (gmn) { ss += sq4(xo0) + sq4(xo1); const f32x4 a = xo0 * *(const LAS f32x4*)(gmp + 128 * bj), c = xo1 * *(const LAS f32x4*)(gmp + 128 * bj + 4);
;                         u32x4 w; w.x = cvt_pk_bf16(a[0], a[1]); w.y = cvt_pk_bf16(a[2], a[3]); w.z = cvt_pk_bf16(c[0], c[1]); w.w = cvt_pk_bf16(c[2], c[3]); *(u32x4*)(AX + off + 128 * bj) = w; }
;                 }
;                 if (gmn) { ss += __shfl_xor(ss, 16); ss += __shfl_xor(ss, 32); if (fq == 0) statx[(size_t)row * 16 + u.pn * 4 + wc] = ss; }
.LBB0_232:
	s_andn2_b64 vcc, exec, s[54:55]
	s_cbranch_vccnz .LBB0_234
	v_pk_fma_f32 v[94:95], v[86:87], v[134:135], v[158:159]
	v_pk_fma_f32 v[90:91], v[78:79], v[130:131], v[154:155]
	ds_write_b128 v208, v[92:95]
	ds_write_b128 v208, v[88:91] offset:16
	ds_read_b128 v[216:219], v210
	ds_read_b128 v[220:223], v210 offset:1152
	s_waitcnt lgkmcnt(0)
	global_store_dwordx4 v108, v[216:219], s[20:21] offset:512
	global_store_dwordx4 v108, v[220:223], s[100:101] offset:512
.LBB0_234:
	s_waitcnt lgkmcnt(0)
	v_lshlrev_b64 v[76:77], 10, v[230:231]
	v_lshl_add_u64 v[78:79], v[76:77], 0, v[224:225]
	v_pk_fma_f32 v[82:83], v[82:83], v[150:151], v[146:147]
	v_pk_fma_f32 v[80:81], v[80:81], v[148:149], v[144:145]
	v_pk_fma_f32 v[86:87], v[74:75], v[142:143], v[138:139]
	v_pk_fma_f32 v[84:85], v[72:73], v[140:141], v[136:137]
	v_lshl_add_u64 v[88:89], v[78:79], 2, s[20:21]
	v_lshl_add_u32 v88, v78, 2, v246
	s_mov_b64 s[54:55], -1
	s_and_b64 vcc, exec, s[46:47]
	v_pk_fma_f32 v[76:77], v[68:69], v[132:133], v[112:113]
	v_pk_fma_f32 v[72:73], v[64:65], v[128:129], v[104:105]
	ds_write_b128 v208, v[80:83]
	ds_write_b128 v208, v[84:87] offset:16
	ds_read_b128 v[216:219], v210
	ds_read_b128 v[220:223], v210 offset:1152
	s_waitcnt lgkmcnt(0)
	global_store_dwordx4 v88, v[216:219], s[20:21]
	global_store_dwordx4 v88, v[220:223], s[100:101]
	s_cbranch_vccnz .LBB0_238
	v_mul_f32_e32 v64, v81, v81
	v_mul_f32_e32 v65, v83, v83
	ds_read_b128 v[90:93], v192
	ds_read_b128 v[94:97], v192 offset:16
	v_fmac_f32_e32 v64, v80, v80
	v_fmac_f32_e32 v65, v82, v82
	v_add_f32_e32 v64, v64, v65
	v_mul_f32_e32 v65, v85, v85
	v_mul_f32_e32 v68, v87, v87
	v_fmac_f32_e32 v65, v84, v84
	v_fmac_f32_e32 v68, v86, v86
	v_add_f32_e32 v65, v65, v68
	v_add_f32_e32 v98, v64, v65
	s_waitcnt lgkmcnt(1)
	v_pk_mul_f32 v[64:65], v[82:83], v[92:93]
	v_pk_mul_f32 v[68:69], v[80:81], v[90:91]
	s_waitcnt lgkmcnt(0)
	v_pk_mul_f32 v[74:75], v[86:87], v[96:97]
	v_pk_mul_f32 v[82:83], v[84:85], v[94:95]
	v_cvt_pk_bf16_f32 v80, v68, v69
	v_cvt_pk_bf16_f32 v81, v64, v65
	v_cvt_pk_bf16_f32 v82, v82, v83
	v_cvt_pk_bf16_f32 v83, v74, v75
	v_lshl_add_u64 v[64:65], v[78:79], 1, s[16:17]
	v_lshl_add_u64 v[64:65], v[204:205], 0, v[64:65]
	v_pk_fma_f32 v[78:79], v[70:71], v[134:135], v[114:115]
	ds_bpermute_b32 v80, v206, v80
	ds_bpermute_b32 v81, v206, v81
	ds_bpermute_b32 v82, v206, v82
	ds_bpermute_b32 v83, v206, v83
	s_waitcnt lgkmcnt(0)
	global_store_dwordx4 v[64:65], v[80:83], off
	v_pk_fma_f32 v[74:75], v[66:67], v[130:131], v[106:107]
	ds_write_b128 v208, v[76:79]
	ds_write_b128 v208, v[72:75] offset:16
	ds_read_b128 v[216:219], v210
	ds_read_b128 v[220:223], v210 offset:1152
	ds_read_b128 v[80:83], v192 offset:512
	s_waitcnt lgkmcnt(0)
	v_pk_mul_f32 v[68:69], v[78:79], v[82:83]
	v_pk_mul_f32 v[84:85], v[76:77], v[80:81]
	ds_read_b128 v[80:83], v192 offset:528
	s_waitcnt lgkmcnt(0)
	v_pk_mul_f32 v[86:87], v[74:75], v[82:83]
	v_pk_mul_f32 v[82:83], v[72:73], v[80:81]
	v_cvt_pk_bf16_f32 v80, v84, v85
	v_cvt_pk_bf16_f32 v81, v68, v69
	s_waitcnt lgkmcnt(0)
	global_store_dwordx4 v88, v[216:219], s[20:21] offset:512
	global_store_dwordx4 v88, v[220:223], s[100:101] offset:512
	v_cvt_pk_bf16_f32 v82, v82, v83
	v_cvt_pk_bf16_f32 v83, v86, v87
	ds_bpermute_b32 v80, v206, v80
	ds_bpermute_b32 v81, v206, v81
	ds_bpermute_b32 v82, v206, v82
	ds_bpermute_b32 v83, v206, v83
	s_waitcnt lgkmcnt(0)
	global_store_dwordx4 v[64:65], v[80:83], off offset:256
	v_mul_f32_e32 v64, v77, v77
	v_mul_f32_e32 v65, v79, v79
	v_fmac_f32_e32 v64, v76, v76
	v_fmac_f32_e32 v65, v78, v78
	v_add_f32_e32 v64, v64, v65
	v_mul_f32_e32 v65, v73, v73
	v_mul_f32_e32 v68, v75, v75
	v_fmac_f32_e32 v65, v72, v72
	v_fmac_f32_e32 v68, v74, v74
	v_add_f32_e32 v65, v65, v68
	v_and_b32_e32 v68, 64, v242
	v_add_f32_e32 v64, v64, v65
	v_xor_b32_e32 v65, 16, v242
	v_add_u32_e32 v68, 64, v68
	v_cmp_lt_i32_e32 vcc, v65, v68
	v_add_f32_e32 v64, v98, v64
	s_nop 0
	v_cndmask_b32_e32 v65, v242, v65, vcc
	v_lshlrev_b32_e32 v65, 2, v65
	ds_bpermute_b32 v65, v65, v64
	s_waitcnt lgkmcnt(0)
	v_add_f32_e32 v64, v64, v65
	v_xor_b32_e32 v65, 32, v242
	v_cmp_lt_i32_e32 vcc, v65, v68
	s_nop 1
	v_cndmask_b32_e32 v65, v242, v65, vcc
	v_lshlrev_b32_e32 v65, 2, v65
	ds_bpermute_b32 v65, v65, v64
	s_and_saveexec_b64 s[54:55], s[44:45]
	s_cbranch_execz .LBB0_237
	v_lshlrev_b64 v[68:69], 6, v[230:231]
	v_lshl_add_u64 v[68:69], s[22:23], 0, v[68:69]
	v_lshl_add_u64 v[68:69], s[76:77], 2, v[68:69]
	s_lshl_b32 s92, s6, 2
	v_lshl_add_u64 v[68:69], v[68:69], 0, s[92:93]
	s_waitcnt lgkmcnt(0)
	v_add_f32_e32 v64, v64, v65
	global_store_dword v[68:69], v64, off

; #define LAS __attribute__((address_space(3)))
; __device__ __forceinline__ unsigned cvt_pk_bf16(float lo, float hi) { const cvt_f32x2_t v = {lo, hi}; const cvt_bf16x2_t b = __builtin_convertvector(v, cvt_bf16x2_t); return __builtin_bit_cast(unsigned, b); }
; __device__ __forceinline__ float sq4(f32x4 v) { return (v[0] * v[0] + v[1] * v[1]) + (v[2] * v[2] + v[3] * v[3]); }
;     __device__ __forceinline__ void operator()(const f32x4 (&acc)[2][2][4][2], const Unit& u, int wr, int wc, int fr, int fq) const {
;     ...
;         for (int ai = 0; ai < 2; ++ai) {
;             f32x4 xr[4][2][2];
; #pragma unroll
;             for (int m = 0; m < 4; ++m) { const size_t off = (size_t)(u.pm * 256 + ai * 128 + wr * 64 + m * 16 + fr) * DM + col0;
; #pragma unroll
;                 for (int bj = 0; bj < 2; ++bj)
; #pragma unroll
;                     for (int n = 0; n < 2; ++n) xr[m][bj][n] = *(const f32x4*)(xin + off + 128 * bj + 4 * n); }
;             asm volatile("" ::: "memory");
; #pragma unroll
;             for (int m = 0; m < 4; ++m) {
;                 const int row = u.pm * 256 + ai * 128 + wr * 64 + m * 16 + fr;
;                 const size_t off = (size_t)row * DM + col0;
;                 float ss = 0.f;
; #pragma unroll
;                 for (int bj = 0; bj < 2; ++bj) {
;                     const f32x4 xo0 = xr[m][bj][0] + *(const LAS f32x4*)(gtp + 128 * bj) * acc[ai][bj][m][0], xo1 = xr[m][bj][1] + *(const LAS f32x4*)(gtp + 128 * bj + 4) * acc[ai][bj][m][1];
;                     *(f32x4*)(xout + off + 128 * bj) = xo0; *(f32x4*)(xout + off + 128 * bj + 4) = xo1;
;                     if (gmn) { ss += sq4(xo0) + sq4(xo1); const f32x4 a = xo0 * *(const LAS f32x4*)(gmp + 128 * bj), c = xo1 * *(const LAS f32x4*)(gmp + 128 * bj + 4);
;                         u32x4 w; w.x = cvt_pk_bf16(a[0], a[1]); w.y = cvt_pk_bf16(a[2], a[3]); w.z = cvt_pk_bf16(c[0], c[1]); w.w = cvt_pk_bf16(c[2], c[3]); *(u32x4*)(AX + off + 128 * bj) = w; }
;                 }
;                 if (gmn) { ss += __shfl_xor(ss, 16); ss += __shfl_xor(ss, 32); if (fq == 0) statx[(size_t)row * 16 + u.pn * 4 + wc] = ss; }
.LBB0_238:
	s_andn2_b64 vcc, exec, s[54:55]
	s_cbranch_vccnz .LBB0_240
	v_pk_fma_f32 v[78:79], v[70:71], v[134:135], v[114:115]
	v_pk_fma_f32 v[74:75], v[66:67], v[130:131], v[106:107]
	ds_write_b128 v208, v[76:79]
	ds_write_b128 v208, v[72:75] offset:16
	ds_read_b128 v[216:219], v210
	ds_read_b128 v[220:223], v210 offset:1152
	s_waitcnt lgkmcnt(0)
	global_store_dwordx4 v88, v[216:219], s[20:21] offset:512
	global_store_dwordx4 v88, v[220:223], s[100:101] offset:512
.LBB0_240:
	v_add_u32_e32 v134, 0x80, v226
	v_ashrrev_i32_e32 v135, 31, v134
	s_waitcnt lgkmcnt(0)
	v_lshlrev_b64 v[64:65], 12, v[134:135]
	v_add_u32_e32 v132, 0x90, v226
	v_lshl_add_u64 v[64:65], v[228:229], 0, v[64:65]
	v_ashrrev_i32_e32 v133, 31, v132
	global_load_dwordx4 v[136:139], v[64:65], off offset:16
	global_load_dwordx4 v[140:143], v[64:65], off
	global_load_dwordx4 v[120:123], v[64:65], off offset:528
	global_load_dwordx4 v[124:127], v[64:65], off offset:512
	v_lshlrev_b64 v[64:65], 12, v[132:133]
	v_add_u32_e32 v130, 0xa0, v226
	v_lshl_add_u64 v[64:65], v[228:229], 0, v[64:65]
	v_ashrrev_i32_e32 v131, 31, v130
	global_load_dwordx4 v[112:115], v[64:65], off offset:16
	global_load_dwordx4 v[116:119], v[64:65], off
	global_load_dwordx4 v[104:107], v[64:65], off offset:528
	global_load_dwordx4 v[108:111], v[64:65], off offset:512
	v_lshlrev_b64 v[64:65], 12, v[130:131]
	v_add_u32_e32 v128, 0xb0, v226
	v_lshl_add_u64 v[64:65], v[228:229], 0, v[64:65]
	v_ashrrev_i32_e32 v129, 31, v128
	global_load_dwordx4 v[96:99], v[64:65], off offset:16
	global_load_dwordx4 v[100:103], v[64:65], off
	global_load_dwordx4 v[88:91], v[64:65], off offset:528
	global_load_dwordx4 v[92:95], v[64:65], off offset:512
	v_lshlrev_b64 v[64:65], 12, v[128:129]
	v_lshl_add_u64 v[68:69], v[228:229], 0, v[64:65]
	global_load_dwordx4 v[72:75], v[68:69], off offset:16
	global_load_dwordx4 v[80:83], v[68:69], off
	global_load_dwordx4 v[64:67], v[68:69], off offset:528
	s_nop 0
	global_load_dwordx4 v[68:71], v[68:69], off offset:512
	v_lshlrev_b64 v[76:77], 10, v[134:135]
	v_lshl_add_u64 v[144:145], v[76:77], 0, v[224:225]
	ds_read_b128 v[84:87], v249
	ds_read_b128 v[76:79], v249 offset:16
	s_and_b64 vcc, exec, s[46:47]
	s_waitcnt vmcnt(15) lgkmcnt(0)
	v_pk_fma_f32 v[58:59], v[58:59], v[78:79], v[138:139]
	s_waitcnt vmcnt(14)
	v_pk_fma_f32 v[62:63], v[62:63], v[86:87], v[142:143]
	v_pk_fma_f32 v[60:61], v[60:61], v[84:85], v[140:141]
	v_pk_fma_f32 v[56:57], v[56:57], v[76:77], v[136:137]
	v_lshl_add_u64 v[136:137], v[144:145], 2, s[20:21]
	v_lshl_add_u32 v136, v144, 2, v246
	v_mov_b32_e32 v140, 0
	v_lshl_add_u64 v[138:139], v[144:145], 1, s[16:17]
	v_lshl_add_u64 v[138:139], v[204:205], 0, v[138:139]
	ds_write_b128 v208, v[60:63]
	ds_write_b128 v208, v[56:59] offset:16
	ds_read_b128 v[216:219], v210
	ds_read_b128 v[220:223], v210 offset:1152
	s_waitcnt lgkmcnt(0)
	global_store_dwordx4 v136, v[216:219], s[20:21]
	global_store_dwordx4 v136, v[220:223], s[100:101]
	s_cbranch_vccnz .LBB0_242
	v_mov_b32_e32 v142, v61
	v_mov_b32_e32 v143, v57
	v_mov_b32_e32 v140, v60
	v_mov_b32_e32 v141, v56
	v_pk_mul_f32 v[142:143], v[142:143], v[142:143]
	v_mov_b32_e32 v144, v63
	v_mov_b32_e32 v145, v59
	v_pk_fma_f32 v[140:141], v[140:141], v[140:141], v[142:143]
	v_mov_b32_e32 v142, v62
	v_mov_b32_e32 v143, v58
	v_pk_mul_f32 v[144:145], v[144:145], v[144:145]
	s_nop 0
	v_pk_fma_f32 v[142:143], v[142:143], v[142:143], v[144:145]
	s_nop 0
	v_pk_add_f32 v[140:141], v[140:141], v[142:143]
	ds_read_b128 v[142:145], v192
	ds_read_b128 v[146:149], v192 offset:16
	v_add_f32_e32 v140, v140, v141
	s_waitcnt lgkmcnt(1)
	v_pk_mul_f32 v[62:63], v[62:63], v[144:145]
	v_pk_mul_f32 v[60:61], v[60:61], v[142:143]
	s_waitcnt lgkmcnt(0)
	v_pk_mul_f32 v[142:143], v[58:59], v[148:149]
	v_pk_mul_f32 v[58:59], v[56:57], v[146:147]
	v_cvt_pk_bf16_f32 v56, v60, v61
	v_cvt_pk_bf16_f32 v57, v62, v63
	v_cvt_pk_bf16_f32 v58, v58, v59
	v_cvt_pk_bf16_f32 v59, v142, v143
	ds_bpermute_b32 v56, v206, v56
	ds_bpermute_b32 v57, v206, v57
	ds_bpermute_b32 v58, v206, v58
	ds_bpermute_b32 v59, v206, v59
	s_waitcnt lgkmcnt(0)
	global_store_dwordx4 v[138:139], v[56:59], off
.LBB0_242:
	ds_read_b128 v[60:63], v249 offset:512
	ds_read_b128 v[56:59], v249 offset:528
	s_and_b64 vcc, exec, s[46:47]
	s_waitcnt vmcnt(14) lgkmcnt(1)
	v_pk_fma_f32 v[54:55], v[54:55], v[62:63], v[126:127]
	v_pk_fma_f32 v[52:53], v[52:53], v[60:61], v[124:125]
	s_waitcnt lgkmcnt(0)
	v_pk_fma_f32 v[50:51], v[50:51], v[58:59], v[122:123]
	v_pk_fma_f32 v[48:49], v[48:49], v[56:57], v[120:121]
	ds_write_b128 v208, v[52:55]
	ds_write_b128 v208, v[48:51] offset:16
	ds_read_b128 v[216:219], v210
	ds_read_b128 v[220:223], v210 offset:1152
	s_waitcnt lgkmcnt(0)
	global_store_dwordx4 v136, v[216:219], s[20:21] offset:512
	global_store_dwordx4 v136, v[220:223], s[100:101] offset:512
	s_cbranch_vccnz .LBB0_246
	ds_read_b128 v[120:123], v192 offset:512
	ds_read_b128 v[124:127], v192 offset:528
	s_waitcnt lgkmcnt(1)
	v_pk_mul_f32 v[120:121], v[52:53], v[120:121]
	s_waitcnt lgkmcnt(0)
	v_pk_mul_f32 v[124:125], v[48:49], v[124:125]
	v_mul_f32_e32 v49, v49, v49
	v_mul_f32_e32 v53, v53, v53
	v_fmac_f32_e32 v49, v48, v48
	v_mul_f32_e32 v48, v51, v51
	v_pk_mul_f32 v[126:127], v[50:51], v[126:127]
	v_fmac_f32_e32 v53, v52, v52
	v_mul_f32_e32 v52, v55, v55
	v_fmac_f32_e32 v48, v50, v50
	v_and_b32_e32 v50, 64, v242
	v_fmac_f32_e32 v52, v54, v54
	v_add_f32_e32 v48, v49, v48
	v_xor_b32_e32 v49, 16, v242
	v_add_u32_e32 v50, 64, v50
	v_add_f32_e32 v52, v53, v52
	v_cmp_lt_i32_e32 vcc, v49, v50
	v_add_f32_e32 v48, v52, v48
	v_add_f32_e32 v48, v140, v48
	v_cndmask_b32_e32 v49, v242, v49, vcc
	v_lshlrev_b32_e32 v49, 2, v49
	ds_bpermute_b32 v49, v49, v48
	v_pk_mul_f32 v[122:123], v[54:55], v[122:123]
	v_cvt_pk_bf16_f32 v120, v120, v121
	v_cvt_pk_bf16_f32 v121, v122, v123
	v_cvt_pk_bf16_f32 v122, v124, v125
	s_waitcnt lgkmcnt(0)
	v_add_f32_e32 v48, v48, v49
	v_xor_b32_e32 v49, 32, v242
	v_cmp_lt_i32_e32 vcc, v49, v50
	v_cvt_pk_bf16_f32 v123, v126, v127
	ds_bpermute_b32 v120, v206, v120
	ds_bpermute_b32 v121, v206, v121
	ds_bpermute_b32 v122, v206, v122
	ds_bpermute_b32 v123, v206, v123
	s_waitcnt lgkmcnt(0)
	global_store_dwordx4 v[138:139], v[120:123], off offset:256
	v_cndmask_b32_e32 v49, v242, v49, vcc
	v_lshlrev_b32_e32 v49, 2, v49
	ds_bpermute_b32 v49, v49, v48
	s_and_saveexec_b64 s[54:55], s[44:45]
	s_cbranch_execz .LBB0_245
	v_lshlrev_b64 v[50:51], 6, v[134:135]
	v_lshl_add_u64 v[50:51], s[22:23], 0, v[50:51]
	v_lshl_add_u64 v[50:51], s[76:77], 2, v[50:51]
	s_lshl_b32 s92, s6, 2
	v_lshl_add_u64 v[50:51], v[50:51], 0, s[92:93]
	s_waitcnt lgkmcnt(0)
	v_add_f32_e32 v48, v48, v49
	global_store_dword v[50:51], v48, off

; #define LAS __attribute__((address_space(3)))
; __device__ __forceinline__ unsigned cvt_pk_bf16(float lo, float hi) { const cvt_f32x2_t v = {lo, hi}; const cvt_bf16x2_t b = __builtin_convertvector(v, cvt_bf16x2_t); return __builtin_bit_cast(unsigned, b); }
; __device__ __forceinline__ float sq4(f32x4 v) { return (v[0] * v[0] + v[1] * v[1]) + (v[2] * v[2] + v[3] * v[3]); }
;     __device__ __forceinline__ void operator()(const f32x4 (&acc)[2][2][4][2], const Unit& u, int wr, int wc, int fr, int fq) const {
;     ...
;             for (int m = 0; m < 4; ++m) {
;                 const int row = u.pm * 256 + ai * 128 + wr * 64 + m * 16 + fr;
;                 const size_t off = (size_t)row * DM + col0;
;                 float ss = 0.f;
; #pragma unroll
;                 for (int bj = 0; bj < 2; ++bj) {
;                     const f32x4 xo0 = xr[m][bj][0] + *(const LAS f32x4*)(gtp + 128 * bj) * acc[ai][bj][m][0], xo1 = xr[m][bj][1] + *(const LAS f32x4*)(gtp + 128 * bj + 4) * acc[ai][bj][m][1];
;                     *(f32x4*)(xout + off + 128 * bj) = xo0; *(f32x4*)(xout + off + 128 * bj + 4) = xo1;
;                     if (gmn) { ss += sq4(xo0) + sq4(xo1); const f32x4 a = xo0 * *(const LAS f32x4*)(gmp + 128 * bj), c = xo1 * *(const LAS f32x4*)(gmp + 128 * bj + 4);
;                         u32x4 w; w.x = cvt_pk_bf16(a[0], a[1]); w.y = cvt_pk_bf16(a[2], a[3]); w.z = cvt_pk_bf16(c[0], c[1]); w.w = cvt_pk_bf16(c[2], c[3]); *(u32x4*)(AX + off + 128 * bj) = w; }
;                 }
;                 if (gmn) { ss += __shfl_xor(ss, 16); ss += __shfl_xor(ss, 32); if (fq == 0) statx[(size_t)row * 16 + u.pn * 4 + wc] = ss; }
.LBB0_246:
	s_waitcnt lgkmcnt(0)
	v_lshlrev_b64 v[48:49], 10, v[132:133]
	v_lshl_add_u64 v[120:121], v[48:49], 0, v[224:225]
	s_waitcnt vmcnt(14)
	v_pk_fma_f32 v[48:49], v[46:47], v[86:87], v[118:119]
	v_pk_fma_f32 v[46:47], v[44:45], v[84:85], v[116:117]
	v_pk_fma_f32 v[52:53], v[42:43], v[78:79], v[114:115]
	v_pk_fma_f32 v[50:51], v[40:41], v[76:77], v[112:113]
	v_lshl_add_u64 v[54:55], v[120:121], 2, s[20:21]
	v_lshl_add_u32 v54, v120, 2, v246
	s_mov_b64 s[54:55], -1
	s_and_b64 vcc, exec, s[46:47]
	s_waitcnt vmcnt(12)
	v_pk_fma_f32 v[44:45], v[36:37], v[60:61], v[108:109]
	v_pk_fma_f32 v[40:41], v[28:29], v[56:57], v[104:105]
	ds_write_b128 v208, v[46:49]
	ds_write_b128 v208, v[50:53] offset:16
	ds_read_b128 v[216:219], v210
	ds_read_b128 v[220:223], v210 offset:1152
	s_waitcnt lgkmcnt(0)
	global_store_dwordx4 v54, v[216:219], s[20:21]
	global_store_dwordx4 v54, v[220:223], s[100:101]
	s_cbranch_vccnz .LBB0_250
	v_mul_f32_e32 v28, v47, v47
	v_mul_f32_e32 v29, v49, v49
	ds_read_b128 v[112:115], v192
	ds_read_b128 v[116:119], v192 offset:16
	v_fmac_f32_e32 v28, v46, v46
	v_fmac_f32_e32 v29, v48, v48
	v_add_f32_e32 v28, v28, v29
	v_mul_f32_e32 v29, v51, v51
	v_mul_f32_e32 v36, v53, v53
	v_fmac_f32_e32 v29, v50, v50
	v_fmac_f32_e32 v36, v52, v52
	v_add_f32_e32 v29, v29, v36
	v_add_f32_e32 v108, v28, v29
	s_waitcnt lgkmcnt(1)
	v_pk_mul_f32 v[28:29], v[48:49], v[114:115]
	v_pk_mul_f32 v[36:37], v[46:47], v[112:113]
	s_waitcnt lgkmcnt(0)
	v_pk_mul_f32 v[42:43], v[52:53], v[118:119]
	v_pk_mul_f32 v[48:49], v[50:51], v[116:117]
	v_cvt_pk_bf16_f32 v46, v36, v37
	v_cvt_pk_bf16_f32 v47, v28, v29
	v_cvt_pk_bf16_f32 v48, v48, v49
	v_cvt_pk_bf16_f32 v49, v42, v43
	v_lshl_add_u64 v[28:29], v[120:121], 1, s[16:17]
	ds_bpermute_b32 v46, v206, v46
	ds_bpermute_b32 v47, v206, v47
	ds_bpermute_b32 v48, v206, v48
	ds_bpermute_b32 v49, v206, v49
	s_waitcnt lgkmcnt(0)
	v_lshl_add_u64 v[28:29], v[204:205], 0, v[28:29]
	global_store_dwordx4 v[28:29], v[46:49], off
	v_pk_fma_f32 v[42:43], v[30:31], v[58:59], v[106:107]
	s_nop 0
	v_pk_fma_f32 v[46:47], v[38:39], v[62:63], v[110:111]
	ds_write_b128 v208, v[44:47]
	ds_write_b128 v208, v[40:43] offset:16
	ds_read_b128 v[216:219], v210
	ds_read_b128 v[220:223], v210 offset:1152
	ds_read_b128 v[48:51], v192 offset:512
	s_waitcnt lgkmcnt(0)
	v_pk_mul_f32 v[36:37], v[46:47], v[50:51]
	v_pk_mul_f32 v[52:53], v[44:45], v[48:49]
	ds_read_b128 v[48:51], v192 offset:528
	s_waitcnt lgkmcnt(0)
	v_pk_mul_f32 v[104:105], v[42:43], v[50:51]
	v_pk_mul_f32 v[50:51], v[40:41], v[48:49]
	v_cvt_pk_bf16_f32 v48, v52, v53
	v_cvt_pk_bf16_f32 v49, v36, v37
	s_waitcnt lgkmcnt(0)
	global_store_dwordx4 v54, v[216:219], s[20:21] offset:512
	global_store_dwordx4 v54, v[220:223], s[100:101] offset:512
	v_cvt_pk_bf16_f32 v50, v50, v51
	v_cvt_pk_bf16_f32 v51, v104, v105
	ds_bpermute_b32 v48, v206, v48
	ds_bpermute_b32 v49, v206, v49
	ds_bpermute_b32 v50, v206, v50
	ds_bpermute_b32 v51, v206, v51
	s_waitcnt lgkmcnt(0)
	global_store_dwordx4 v[28:29], v[48:51], off offset:256
	v_mul_f32_e32 v28, v45, v45
	v_mul_f32_e32 v29, v47, v47
	v_fmac_f32_e32 v28, v44, v44
	v_fmac_f32_e32 v29, v46, v46
	v_add_f32_e32 v28, v28, v29
	v_mul_f32_e32 v29, v41, v41
	v_mul_f32_e32 v36, v43, v43
	v_fmac_f32_e32 v29, v40, v40
	v_fmac_f32_e32 v36, v42, v42
	v_add_f32_e32 v29, v29, v36
	v_and_b32_e32 v36, 64, v242
	v_add_f32_e32 v28, v28, v29
	v_xor_b32_e32 v29, 16, v242
	v_add_u32_e32 v36, 64, v36
	v_cmp_lt_i32_e32 vcc, v29, v36
	v_add_f32_e32 v28, v108, v28
	s_nop 0
	v_cndmask_b32_e32 v29, v242, v29, vcc
	v_lshlrev_b32_e32 v29, 2, v29
	ds_bpermute_b32 v29, v29, v28
	s_waitcnt lgkmcnt(0)
	v_add_f32_e32 v28, v28, v29
	v_xor_b32_e32 v29, 32, v242
	v_cmp_lt_i32_e32 vcc, v29, v36
	s_nop 1
	v_cndmask_b32_e32 v29, v242, v29, vcc
	v_lshlrev_b32_e32 v29, 2, v29
	ds_bpermute_b32 v29, v29, v28
	s_and_saveexec_b64 s[54:55], s[44:45]
	s_cbranch_execz .LBB0_249
	v_lshlrev_b64 v[36:37], 6, v[132:133]
	v_lshl_add_u64 v[36:37], s[22:23], 0, v[36:37]
	v_lshl_add_u64 v[36:37], s[76:77], 2, v[36:37]
	s_lshl_b32 s92, s6, 2
	v_lshl_add_u64 v[36:37], v[36:37], 0, s[92:93]
	s_waitcnt lgkmcnt(0)
	v_add_f32_e32 v28, v28, v29
	global_store_dword v[36:37], v28, off

; #define LAS __attribute__((address_space(3)))
; __device__ __forceinline__ unsigned cvt_pk_bf16(float lo, float hi) { const cvt_f32x2_t v = {lo, hi}; const cvt_bf16x2_t b = __builtin_convertvector(v, cvt_bf16x2_t); return __builtin_bit_cast(unsigned, b); }
; __device__ __forceinline__ float sq4(f32x4 v) { return (v[0] * v[0] + v[1] * v[1]) + (v[2] * v[2] + v[3] * v[3]); }
;     __device__ __forceinline__ void operator()(const f32x4 (&acc)[2][2][4][2], const Unit& u, int wr, int wc, int fr, int fq) const {
;     ...
;             for (int m = 0; m < 4; ++m) {
;                 const int row = u.pm * 256 + ai * 128 + wr * 64 + m * 16 + fr;
;                 const size_t off = (size_t)row * DM + col0;
;                 float ss = 0.f;
; #pragma unroll
;                 for (int bj = 0; bj < 2; ++bj) {
;                     const f32x4 xo0 = xr[m][bj][0] + *(const LAS f32x4*)(gtp + 128 * bj) * acc[ai][bj][m][0], xo1 = xr[m][bj][1] + *(const LAS f32x4*)(gtp + 128 * bj + 4) * acc[ai][bj][m][1];
;                     *(f32x4*)(xout + off + 128 * bj) = xo0; *(f32x4*)(xout + off + 128 * bj + 4) = xo1;
;                     if (gmn) { ss += sq4(xo0) + sq4(xo1); const f32x4 a = xo0 * *(const LAS f32x4*)(gmp + 128 * bj), c = xo1 * *(const LAS f32x4*)(gmp + 128 * bj + 4);
;                         u32x4 w; w.x = cvt_pk_bf16(a[0], a[1]); w.y = cvt_pk_bf16(a[2], a[3]); w.z = cvt_pk_bf16(c[0], c[1]); w.w = cvt_pk_bf16(c[2], c[3]); *(u32x4*)(AX + off + 128 * bj) = w; }
;                 }
;                 if (gmn) { ss += __shfl_xor(ss, 16); ss += __shfl_xor(ss, 32); if (fq == 0) statx[(size_t)row * 16 + u.pn * 4 + wc] = ss; }
.LBB0_250:
	s_andn2_b64 vcc, exec, s[54:55]
	s_cbranch_vccnz .LBB0_252
	v_pk_fma_f32 v[46:47], v[38:39], v[62:63], v[110:111]
	v_pk_fma_f32 v[42:43], v[30:31], v[58:59], v[106:107]
	ds_write_b128 v208, v[44:47]
	ds_write_b128 v208, v[40:43] offset:16
	ds_read_b128 v[216:219], v210
	ds_read_b128 v[220:223], v210 offset:1152
	s_waitcnt lgkmcnt(0)
	global_store_dwordx4 v54, v[216:219], s[20:21] offset:512
	global_store_dwordx4 v54, v[220:223], s[100:101] offset:512
.LBB0_252:
	s_waitcnt lgkmcnt(0)
	v_lshlrev_b64 v[28:29], 10, v[130:131]
	v_lshl_add_u64 v[30:31], v[28:29], 0, v[224:225]
	s_waitcnt vmcnt(12)
	v_pk_fma_f32 v[34:35], v[34:35], v[86:87], v[102:103]
	v_pk_fma_f32 v[32:33], v[32:33], v[84:85], v[100:101]
	v_pk_fma_f32 v[38:39], v[26:27], v[78:79], v[98:99]
	v_pk_fma_f32 v[36:37], v[24:25], v[76:77], v[96:97]
	v_lshl_add_u64 v[40:41], v[30:31], 2, s[20:21]
	v_lshl_add_u32 v40, v30, 2, v246
	s_mov_b64 s[54:55], -1
	s_and_b64 vcc, exec, s[46:47]
	s_waitcnt vmcnt(10)
	v_pk_fma_f32 v[28:29], v[20:21], v[60:61], v[92:93]
	v_pk_fma_f32 v[24:25], v[12:13], v[56:57], v[88:89]
	ds_write_b128 v208, v[32:35]
	ds_write_b128 v208, v[36:39] offset:16
	ds_read_b128 v[216:219], v210
	ds_read_b128 v[220:223], v210 offset:1152
	s_waitcnt lgkmcnt(0)
	global_store_dwordx4 v40, v[216:219], s[20:21]
	global_store_dwordx4 v40, v[220:223], s[100:101]
	s_cbranch_vccnz .LBB0_256
	v_mul_f32_e32 v12, v33, v33
	v_mul_f32_e32 v13, v35, v35
	ds_read_b128 v[42:45], v192
	ds_read_b128 v[46:49], v192 offset:16
	v_fmac_f32_e32 v12, v32, v32
	v_fmac_f32_e32 v13, v34, v34
	v_add_f32_e32 v12, v12, v13
	v_mul_f32_e32 v13, v37, v37
	v_mul_f32_e32 v20, v39, v39
	v_fmac_f32_e32 v13, v36, v36
	v_fmac_f32_e32 v20, v38, v38
	v_add_f32_e32 v13, v13, v20
	v_add_f32_e32 v50, v12, v13
	s_waitcnt lgkmcnt(1)
	v_pk_mul_f32 v[12:13], v[34:35], v[44:45]
	v_pk_mul_f32 v[20:21], v[32:33], v[42:43]
	s_waitcnt lgkmcnt(0)
	v_pk_mul_f32 v[26:27], v[38:39], v[48:49]
	v_pk_mul_f32 v[34:35], v[36:37], v[46:47]
	v_cvt_pk_bf16_f32 v32, v20, v21
	v_cvt_pk_bf16_f32 v33, v12, v13
	v_cvt_pk_bf16_f32 v34, v34, v35
	v_cvt_pk_bf16_f32 v35, v26, v27
	v_lshl_add_u64 v[12:13], v[30:31], 1, s[16:17]
	v_lshl_add_u64 v[12:13], v[204:205], 0, v[12:13]
	v_pk_fma_f32 v[30:31], v[22:23], v[62:63], v[94:95]
	ds_bpermute_b32 v32, v206, v32
	ds_bpermute_b32 v33, v206, v33
	ds_bpermute_b32 v34, v206, v34
	ds_bpermute_b32 v35, v206, v35
	s_waitcnt lgkmcnt(0)
	global_store_dwordx4 v[12:13], v[32:35], off
	v_pk_fma_f32 v[26:27], v[14:15], v[58:59], v[90:91]
	ds_write_b128 v208, v[28:31]
	ds_write_b128 v208, v[24:27] offset:16
	ds_read_b128 v[216:219], v210
	ds_read_b128 v[220:223], v210 offset:1152
	ds_read_b128 v[32:35], v192 offset:512
	s_waitcnt lgkmcnt(0)
	v_pk_mul_f32 v[20:21], v[30:31], v[34:35]
	v_pk_mul_f32 v[36:37], v[28:29], v[32:33]
	ds_read_b128 v[32:35], v192 offset:528
	s_waitcnt lgkmcnt(0)
	v_pk_mul_f32 v[38:39], v[26:27], v[34:35]
	v_pk_mul_f32 v[34:35], v[24:25], v[32:33]
	v_cvt_pk_bf16_f32 v32, v36, v37
	v_cvt_pk_bf16_f32 v33, v20, v21
	s_waitcnt lgkmcnt(0)
	global_store_dwordx4 v40, v[216:219], s[20:21] offset:512
	global_store_dwordx4 v40, v[220:223], s[100:101] offset:512
	v_cvt_pk_bf16_f32 v34, v34, v35
	v_cvt_pk_bf16_f32 v35, v38, v39
	ds_bpermute_b32 v32, v206, v32
	ds_bpermute_b32 v33, v206, v33
	ds_bpermute_b32 v34, v206, v34
	ds_bpermute_b32 v35, v206, v35
	s_waitcnt lgkmcnt(0)
	global_store_dwordx4 v[12:13], v[32:35], off offset:256
	v_mul_f32_e32 v12, v29, v29
	v_mul_f32_e32 v13, v31, v31
	v_fmac_f32_e32 v12, v28, v28
	v_fmac_f32_e32 v13, v30, v30
	v_add_f32_e32 v12, v12, v13
	v_mul_f32_e32 v13, v25, v25
	v_mul_f32_e32 v20, v27, v27
	v_fmac_f32_e32 v13, v24, v24
	v_fmac_f32_e32 v20, v26, v26
	v_add_f32_e32 v13, v13, v20
	v_and_b32_e32 v20, 64, v242
	v_add_f32_e32 v12, v12, v13
	v_xor_b32_e32 v13, 16, v242
	v_add_u32_e32 v20, 64, v20
	v_cmp_lt_i32_e32 vcc, v13, v20
	v_add_f32_e32 v12, v50, v12
	s_nop 0
	v_cndmask_b32_e32 v13, v242, v13, vcc
	v_lshlrev_b32_e32 v13, 2, v13
	ds_bpermute_b32 v13, v13, v12
	s_waitcnt lgkmcnt(0)
	v_add_f32_e32 v12, v12, v13
	v_xor_b32_e32 v13, 32, v242
	v_cmp_lt_i32_e32 vcc, v13, v20
	s_nop 1
	v_cndmask_b32_e32 v13, v242, v13, vcc
	v_lshlrev_b32_e32 v13, 2, v13
	ds_bpermute_b32 v13, v13, v12
	s_and_saveexec_b64 s[54:55], s[44:45]
	s_cbranch_execz .LBB0_255
	v_lshlrev_b64 v[20:21], 6, v[130:131]
	v_lshl_add_u64 v[20:21], s[22:23], 0, v[20:21]
	v_lshl_add_u64 v[20:21], s[76:77], 2, v[20:21]
	s_lshl_b32 s92, s6, 2
	v_lshl_add_u64 v[20:21], v[20:21], 0, s[92:93]
	s_waitcnt lgkmcnt(0)
	v_add_f32_e32 v12, v12, v13
	global_store_dword v[20:21], v12, off

; #define LAS __attribute__((address_space(3)))
;     __device__ __forceinline__ void operator()(const f32x4 (&acc)[2][2][4][2], const Unit& u, int wr, int wc, int fr, int fq) const {
;     ...
;                 for (int bj = 0; bj < 2; ++bj) {
;                     const f32x4 xo0 = xr[m][bj][0] + *(const LAS f32x4*)(gtp + 128 * bj) * acc[ai][bj][m][0], xo1 = xr[m][bj][1] + *(const LAS f32x4*)(gtp + 128 * bj + 4) * acc[ai][bj][m][1];
;                     *(f32x4*)(xout + off + 128 * bj) = xo0; *(f32x4*)(xout + off + 128 * bj + 4) = xo1;
.LBB0_256:
	s_andn2_b64 vcc, exec, s[54:55]
	s_cbranch_vccnz .LBB0_258
	v_pk_fma_f32 v[30:31], v[22:23], v[62:63], v[94:95]
	v_pk_fma_f32 v[26:27], v[14:15], v[58:59], v[90:91]
	ds_write_b128 v208, v[28:31]
	ds_write_b128 v208, v[24:27] offset:16
	ds_read_b128 v[216:219], v210
	ds_read_b128 v[220:223], v210 offset:1152
	s_waitcnt lgkmcnt(0)
	global_store_dwordx4 v40, v[216:219], s[20:21] offset:512
	global_store_dwordx4 v40, v[220:223], s[100:101] offset:512
.LBB0_258:
	s_waitcnt lgkmcnt(0)
	v_lshlrev_b64 v[12:13], 10, v[128:129]
	v_lshl_add_u64 v[14:15], v[12:13], 0, v[224:225]
	s_waitcnt vmcnt(10)
	v_pk_fma_f32 v[18:19], v[18:19], v[86:87], v[82:83]
	v_pk_fma_f32 v[16:17], v[16:17], v[84:85], v[80:81]
	v_pk_fma_f32 v[22:23], v[10:11], v[78:79], v[74:75]
	v_pk_fma_f32 v[20:21], v[8:9], v[76:77], v[72:73]
	v_lshl_add_u64 v[24:25], v[14:15], 2, s[20:21]
	v_lshl_add_u32 v24, v14, 2, v246
	s_mov_b64 s[54:55], -1
	s_and_b64 vcc, exec, s[46:47]
	s_waitcnt vmcnt(8)
	v_pk_fma_f32 v[12:13], v[4:5], v[60:61], v[68:69]
	v_pk_fma_f32 v[8:9], v[0:1], v[56:57], v[64:65]
	ds_write_b128 v208, v[16:19]
	ds_write_b128 v208, v[20:23] offset:16
	ds_read_b128 v[216:219], v210
	ds_read_b128 v[220:223], v210 offset:1152
	s_waitcnt lgkmcnt(0)
	global_store_dwordx4 v24, v[216:219], s[20:21]
	global_store_dwordx4 v24, v[220:223], s[100:101]
	s_cbranch_vccz .LBB0_265
	s_andn2_b64 vcc, exec, s[54:55]
	s_cbranch_vccz .LBB0_268

; #define LAS __attribute__((address_space(3)))
; __device__ __forceinline__ unsigned cvt_pk_bf16(float lo, float hi) { const cvt_f32x2_t v = {lo, hi}; const cvt_bf16x2_t b = __builtin_convertvector(v, cvt_bf16x2_t); return __builtin_bit_cast(unsigned, b); }
; __device__ __forceinline__ float sq4(f32x4 v) { return (v[0] * v[0] + v[1] * v[1]) + (v[2] * v[2] + v[3] * v[3]); }
;     __device__ __forceinline__ void operator()(const f32x4 (&acc)[2][2][4][2], const Unit& u, int wr, int wc, int fr, int fq) const {
;     ...
;                 for (int bj = 0; bj < 2; ++bj) {
;                     const f32x4 xo0 = xr[m][bj][0] + *(const LAS f32x4*)(gtp + 128 * bj) * acc[ai][bj][m][0], xo1 = xr[m][bj][1] + *(const LAS f32x4*)(gtp + 128 * bj + 4) * acc[ai][bj][m][1];
;                     *(f32x4*)(xout + off + 128 * bj) = xo0; *(f32x4*)(xout + off + 128 * bj + 4) = xo1;
;                     if (gmn) { ss += sq4(xo0) + sq4(xo1); const f32x4 a = xo0 * *(const LAS f32x4*)(gmp + 128 * bj), c = xo1 * *(const LAS f32x4*)(gmp + 128 * bj + 4);
;                         u32x4 w; w.x = cvt_pk_bf16(a[0], a[1]); w.y = cvt_pk_bf16(a[2], a[3]); w.z = cvt_pk_bf16(c[0], c[1]); w.w = cvt_pk_bf16(c[2], c[3]); *(u32x4*)(AX + off + 128 * bj) = w; }
;                 }
;                 if (gmn) { ss += __shfl_xor(ss, 16); ss += __shfl_xor(ss, 32); if (fq == 0) statx[(size_t)row * 16 + u.pn * 4 + wc] = ss; }
.LBB0_265:
	v_mul_f32_e32 v0, v17, v17
	v_mul_f32_e32 v1, v19, v19
	ds_read_b128 v[26:29], v192
	ds_read_b128 v[30:33], v192 offset:16
	v_fmac_f32_e32 v0, v16, v16
	v_fmac_f32_e32 v1, v18, v18
	v_add_f32_e32 v0, v0, v1
	v_mul_f32_e32 v1, v21, v21
	v_mul_f32_e32 v4, v23, v23
	v_fmac_f32_e32 v1, v20, v20
	v_fmac_f32_e32 v4, v22, v22
	v_add_f32_e32 v1, v1, v4
	v_add_f32_e32 v34, v0, v1
	s_waitcnt lgkmcnt(1)
	v_pk_mul_f32 v[0:1], v[18:19], v[28:29]
	v_pk_mul_f32 v[4:5], v[16:17], v[26:27]
	s_waitcnt lgkmcnt(0)
	v_pk_mul_f32 v[10:11], v[22:23], v[32:33]
	v_pk_mul_f32 v[18:19], v[20:21], v[30:31]
	v_cvt_pk_bf16_f32 v16, v4, v5
	v_cvt_pk_bf16_f32 v17, v0, v1
	v_cvt_pk_bf16_f32 v18, v18, v19
	v_cvt_pk_bf16_f32 v19, v10, v11
	v_lshl_add_u64 v[0:1], v[14:15], 1, s[16:17]
	v_lshl_add_u64 v[0:1], v[204:205], 0, v[0:1]
	v_pk_fma_f32 v[14:15], v[6:7], v[62:63], v[70:71]
	ds_bpermute_b32 v16, v206, v16
	ds_bpermute_b32 v17, v206, v17
	ds_bpermute_b32 v18, v206, v18
	ds_bpermute_b32 v19, v206, v19
	s_waitcnt lgkmcnt(0)
	global_store_dwordx4 v[0:1], v[16:19], off
	v_pk_fma_f32 v[10:11], v[2:3], v[58:59], v[66:67]
	ds_write_b128 v208, v[12:15]
	ds_write_b128 v208, v[8:11] offset:16
	ds_read_b128 v[216:219], v210
	ds_read_b128 v[220:223], v210 offset:1152
	ds_read_b128 v[16:19], v192 offset:512
	s_waitcnt lgkmcnt(0)
	v_pk_mul_f32 v[4:5], v[14:15], v[18:19]
	v_pk_mul_f32 v[20:21], v[12:13], v[16:17]
	ds_read_b128 v[16:19], v192 offset:528
	s_waitcnt lgkmcnt(0)
	v_pk_mul_f32 v[22:23], v[10:11], v[18:19]
	v_pk_mul_f32 v[18:19], v[8:9], v[16:17]
	v_cvt_pk_bf16_f32 v16, v20, v21
	v_cvt_pk_bf16_f32 v17, v4, v5
	s_waitcnt lgkmcnt(0)
	global_store_dwordx4 v24, v[216:219], s[20:21] offset:512
	global_store_dwordx4 v24, v[220:223], s[100:101] offset:512
	v_cvt_pk_bf16_f32 v18, v18, v19
	v_cvt_pk_bf16_f32 v19, v22, v23
	ds_bpermute_b32 v16, v206, v16
	ds_bpermute_b32 v17, v206, v17
	ds_bpermute_b32 v18, v206, v18
	ds_bpermute_b32 v19, v206, v19
	s_waitcnt lgkmcnt(0)
	global_store_dwordx4 v[0:1], v[16:19], off offset:256
	v_mul_f32_e32 v0, v13, v13
	v_mul_f32_e32 v1, v15, v15
	v_fmac_f32_e32 v0, v12, v12
	v_fmac_f32_e32 v1, v14, v14
	v_add_f32_e32 v0, v0, v1
	v_mul_f32_e32 v1, v9, v9
	v_mul_f32_e32 v4, v11, v11
	v_fmac_f32_e32 v1, v8, v8
	v_fmac_f32_e32 v4, v10, v10
	v_add_f32_e32 v1, v1, v4
	v_and_b32_e32 v4, 64, v242
	v_add_f32_e32 v0, v0, v1
	v_xor_b32_e32 v1, 16, v242
	v_add_u32_e32 v4, 64, v4
	v_cmp_lt_i32_e32 vcc, v1, v4
	v_add_f32_e32 v0, v34, v0
	s_nop 0
	v_cndmask_b32_e32 v1, v242, v1, vcc
	v_lshlrev_b32_e32 v1, 2, v1
	ds_bpermute_b32 v1, v1, v0
	s_waitcnt lgkmcnt(0)
	v_add_f32_e32 v0, v0, v1
	v_xor_b32_e32 v1, 32, v242
	v_cmp_lt_i32_e32 vcc, v1, v4
	s_nop 1
	v_cndmask_b32_e32 v1, v242, v1, vcc
	v_lshlrev_b32_e32 v1, 2, v1
	ds_bpermute_b32 v1, v1, v0
	s_and_saveexec_b64 s[46:47], s[44:45]
	s_cbranch_execz .LBB0_267
	v_lshlrev_b64 v[4:5], 6, v[128:129]
	v_lshl_add_u64 v[4:5], s[22:23], 0, v[4:5]
	v_lshl_add_u64 v[4:5], s[76:77], 2, v[4:5]
	s_lshl_b32 s92, s6, 2
	v_lshl_add_u64 v[4:5], v[4:5], 0, s[92:93]
	s_waitcnt lgkmcnt(0)
	v_add_f32_e32 v0, v0, v1
	global_store_dword v[4:5], v0, off

; #define LAS __attribute__((address_space(3)))
;     __device__ __forceinline__ void operator()(const f32x4 (&acc)[2][2][4][2], const Unit& u, int wr, int wc, int fr, int fq) const {
;     ...
;                     const f32x4 xo0 = xr[m][bj][0] + *(const LAS f32x4*)(gtp + 128 * bj) * acc[ai][bj][m][0], xo1 = xr[m][bj][1] + *(const LAS f32x4*)(gtp + 128 * bj + 4) * acc[ai][bj][m][1];
;                     *(f32x4*)(xout + off + 128 * bj) = xo0; *(f32x4*)(xout + off + 128 * bj + 4) = xo1;
.LBB0_268:
	v_pk_fma_f32 v[14:15], v[6:7], v[62:63], v[70:71]
	v_pk_fma_f32 v[10:11], v[2:3], v[58:59], v[66:67]
	ds_write_b128 v208, v[12:15]
	ds_write_b128 v208, v[8:11] offset:16
	ds_read_b128 v[216:219], v210
	ds_read_b128 v[220:223], v210 offset:1152
	s_waitcnt lgkmcnt(0)
	global_store_dwordx4 v24, v[216:219], s[20:21] offset:512
	global_store_dwordx4 v24, v[220:223], s[100:101] offset:512
	ds_read_b32 v216, v252
	ds_read_b32 v218, v252 offset:256
	ds_read_b32 v220, v252 offset:512
	ds_read_b32 v222, v252 offset:768
	v_mov_b32_e32 v217, v193
	v_mov_b32_e32 v219, v193
	v_mov_b32_e32 v221, v193
	v_mov_b32_e32 v223, v193
	s_waitcnt lgkmcnt(0)
	s_andn2_b64 vcc, exec, s[42:43]
	s_mov_b64 s[42:43], -1
	s_cbranch_vccnz .LBB0_201

; #define LAS __attribute__((address_space(3)))
;     __device__ __forceinline__ void operator()(const f32x4 (&acc)[2][2][4][2], const Unit& u, int wr, int wc, int fr, int fq) const {
;         const int b = u.pm >> 3, col0 = u.pn * 256 + wc * 32 + 8 * fq;
;         { const int t = (wr * 4 + wc) * 64 + fq * 16 + fr;
;           if (t < 64) ((LAS f32x4*)gl)[t] = *(const f32x4*)(gate + (size_t)b * gate_ld + u.pn * 256 + 4 * t);
;           else if (t < 128 && gmn) ((LAS f32x4*)gl)[t] = *(const f32x4*)(gmn + (size_t)b * DM + u.pn * 256 + 4 * (t - 64));
;           asm volatile("s_waitcnt vmcnt(0) lgkmcnt(0)" ::: "memory"); __builtin_amdgcn_s_barrier(); asm volatile("" ::: "memory"); }
;         const LAS float* gtp = gl + wc * 32 + 8 * fq; const LAS float* gmp = gl + 256 + wc * 32 + 8 * fq;
.LBB0_319:
	s_mul_i32 s100, s40, 36
	s_add_i32 s100, s100, 0x24000
	s_cmp_eq_u32 s40, 0x1c0
	s_cselect_b32 s100, 0x20c00, s100
	s_lshl_b32 s101, s40, 4
	s_add_i32 s101, s101, 0x21800
	v_lshrrev_b32_e32 v210, 3, v242
	v_and_b32_e32 v246, 7, v242
	v_mul_u32_u24_e32 v210, 0x90, v210
	v_lshl_add_u32 v210, v246, 4, v210
	v_add_u32_e32 v210, s100, v210
	v_mul_u32_u24_e32 v208, 0x90, v211
	v_lshl_add_u32 v208, v207, 5, v208
	v_add_u32_e32 v208, s100, v208
	v_lshrrev_b32_e32 v252, 3, v242
	v_sub_u32_e32 v252, v252, v211
	v_lshlrev_b32_e32 v252, 12, v252
	v_lshl_add_u32 v246, v246, 4, v252
	v_lshlrev_b32_e32 v252, 5, v207
	v_sub_u32_e32 v246, v246, v252
	v_lshl_add_u32 v252, v242, 2, s101
	ds_write_b32 v252, v216
	ds_write_b32 v252, v218 offset:256
	ds_write_b32 v252, v220 offset:512
	ds_write_b32 v252, v222 offset:768
	s_add_u32 s100, s6, 0x8000
	s_addc_u32 s101, s7, 0
	v_and_b32_e32 v206, 3, v242
	v_lshrrev_b32_e32 v204, 2, v242
	v_lshl_add_u32 v205, v206, 4, v204
	v_sub_u32_e32 v204, v204, v211
	v_sub_u32_e32 v206, v206, v207
	v_lshlrev_b32_e32 v204, 11, v204
	v_lshl_add_u32 v204, v206, 4, v204
	v_lshlrev_b32_e32 v206, 2, v205
	v_ashrrev_i32_e32 v205, 31, v204
	v_mov_b32_e32 v106, v211
	v_mov_b32_e32 v250, v207
	s_ashr_i32 s46, s77, 3
	v_lshlrev_b32_e32 v104, 4, v250
	v_add3_u32 v107, s40, v106, v104
	s_lshl_b32 s44, s76, 8
	v_cmp_lt_i32_e32 vcc, 63, v107
	s_mov_b64 s[56:57], 0
	s_and_saveexec_b64 s[54:55], vcc
	s_xor_b64 s[54:55], exec, s[54:55]
	s_movk_i32 s63, 0x5ff
	s_cbranch_execnz .LBB0_368
	s_andn2_saveexec_b64 s[54:55], s[54:55]
	s_cbranch_execnz .LBB0_371

; #define LAS __attribute__((address_space(3)))
; __device__ __forceinline__ unsigned cvt_pk_bf16(float lo, float hi) { const cvt_f32x2_t v = {lo, hi}; const cvt_bf16x2_t b = __builtin_convertvector(v, cvt_bf16x2_t); return __builtin_bit_cast(unsigned, b); }
; __device__ __forceinline__ float sq4(f32x4 v) { return (v[0] * v[0] + v[1] * v[1]) + (v[2] * v[2] + v[3] * v[3]); }
;     __device__ __forceinline__ void operator()(const f32x4 (&acc)[2][2][4][2], const Unit& u, int wr, int wc, int fr, int fq) const {
;     ...
; #pragma unroll
;         for (int ai = 0; ai < 2; ++ai) {
;             f32x4 xr[4][2][2];
; #pragma unroll
;             for (int m = 0; m < 4; ++m) { const size_t off = (size_t)(u.pm * 256 + ai * 128 + wr * 64 + m * 16 + fr) * DM + col0;
; #pragma unroll
;                 for (int bj = 0; bj < 2; ++bj)
; #pragma unroll
;                     for (int n = 0; n < 2; ++n) xr[m][bj][n] = *(const f32x4*)(xin + off + 128 * bj + 4 * n); }
;             asm volatile("" ::: "memory");
; #pragma unroll
;             for (int m = 0; m < 4; ++m) {
;                 const int row = u.pm * 256 + ai * 128 + wr * 64 + m * 16 + fr;
;                 const size_t off = (size_t)row * DM + col0;
;                 float ss = 0.f;
; #pragma unroll
;                 for (int bj = 0; bj < 2; ++bj) {
;                     const f32x4 xo0 = xr[m][bj][0] + *(const LAS f32x4*)(gtp + 128 * bj) * acc[ai][bj][m][0], xo1 = xr[m][bj][1] + *(const LAS f32x4*)(gtp + 128 * bj + 4) * acc[ai][bj][m][1];
;                     *(f32x4*)(xout + off + 128 * bj) = xo0; *(f32x4*)(xout + off + 128 * bj + 4) = xo1;
;                     if (gmn) { ss += sq4(xo0) + sq4(xo1); const f32x4 a = xo0 * *(const LAS f32x4*)(gmp + 128 * bj), c = xo1 * *(const LAS f32x4*)(gmp + 128 * bj + 4);
;                         u32x4 w; w.x = cvt_pk_bf16(a[0], a[1]); w.y = cvt_pk_bf16(a[2], a[3]); w.z = cvt_pk_bf16(c[0], c[1]); w.w = cvt_pk_bf16(c[2], c[3]); *(u32x4*)(AX + off + 128 * bj) = w; }
;                 }
;                 if (gmn) { ss += __shfl_xor(ss, 16); ss += __shfl_xor(ss, 32); if (fq == 0) statx[(size_t)row * 16 + u.pn * 4 + wc] = ss; }
.LBB0_323:
	s_or_b64 exec, exec, s[46:47]
	s_or_b32 s44, s44, s9
	v_lshl_add_u32 v224, v250, 3, s44
	s_lshl_b32 s44, s77, 8
	s_add_i32 s44, s44, s8
	v_add_u32_e32 v226, s44, v106
	v_readlane_b32 s44, v255, 48
	v_lshlrev_b32_e32 v104, 5, v250
	v_ashrrev_i32_e32 v225, 31, v224
	v_readlane_b32 s45, v255, 49
	v_ashrrev_i32_e32 v227, 31, v226
	v_add_u32_e32 v249, s41, v104
	v_add_u32_e32 v192, s4, v104
	v_lshl_add_u64 v[228:229], v[224:225], 2, s[44:45]
	v_lshlrev_b64 v[104:105], 12, v[226:227]
	v_add_u32_e32 v234, 16, v226
	s_waitcnt vmcnt(0) lgkmcnt(0)
	s_barrier
	v_lshl_add_u64 v[104:105], v[228:229], 0, v[104:105]
	v_ashrrev_i32_e32 v235, 31, v234
	global_load_dwordx4 v[194:197], v[104:105], off offset:16
	global_load_dwordx4 v[198:201], v[104:105], off
	global_load_dwordx4 v[184:187], v[104:105], off offset:528
	global_load_dwordx4 v[188:191], v[104:105], off offset:512
	v_lshlrev_b64 v[104:105], 12, v[234:235]
	v_add_u32_e32 v232, 32, v226
	v_lshl_add_u64 v[104:105], v[228:229], 0, v[104:105]
	v_ashrrev_i32_e32 v233, 31, v232
	global_load_dwordx4 v[176:179], v[104:105], off offset:16
	global_load_dwordx4 v[180:183], v[104:105], off
	global_load_dwordx4 v[168:171], v[104:105], off offset:528
	global_load_dwordx4 v[172:175], v[104:105], off offset:512
	v_lshlrev_b64 v[104:105], 12, v[232:233]
	v_add_u32_e32 v230, 48, v226
	v_lshl_add_u64 v[104:105], v[228:229], 0, v[104:105]
	v_ashrrev_i32_e32 v231, 31, v230
	global_load_dwordx4 v[160:163], v[104:105], off offset:16
	global_load_dwordx4 v[164:167], v[104:105], off
	global_load_dwordx4 v[152:155], v[104:105], off offset:528
	global_load_dwordx4 v[156:159], v[104:105], off offset:512
	v_lshlrev_b64 v[104:105], 12, v[230:231]
	v_lshl_add_u64 v[112:113], v[228:229], 0, v[104:105]
	global_load_dwordx4 v[136:139], v[112:113], off offset:16
	global_load_dwordx4 v[144:147], v[112:113], off
	global_load_dwordx4 v[104:107], v[112:113], off offset:528
	s_nop 0
	global_load_dwordx4 v[112:115], v[112:113], off offset:512
	v_lshlrev_b64 v[140:141], 10, v[226:227]
	v_lshl_add_u64 v[202:203], v[140:141], 0, v[224:225]
	ds_read_b128 v[148:151], v249
	ds_read_b128 v[140:143], v249 offset:16
	v_lshl_add_u64 v[236:237], v[202:203], 2, s[6:7]
	v_lshl_add_u32 v236, v202, 2, v246
	v_mov_b32_e32 v251, 0
	s_andn2_b64 vcc, exec, s[38:39]
	v_lshl_add_u64 v[238:239], v[202:203], 1, s[16:17]
	v_lshl_add_u64 v[238:239], v[204:205], 0, v[238:239]
	s_waitcnt vmcnt(0) lgkmcnt(0)
	v_pk_fma_f32 v[128:129], v[128:129], v[140:141], v[194:195]
	v_cndmask_b32_e64 v194, 0, 1, s[38:39]
	v_pk_fma_f32 v[134:135], v[134:135], v[150:151], v[200:201]
	v_pk_fma_f32 v[132:133], v[132:133], v[148:149], v[198:199]
	v_pk_fma_f32 v[130:131], v[130:131], v[142:143], v[196:197]
	v_cmp_ne_u32_e64 s[46:47], 1, v194
	ds_write_b128 v208, v[132:135]
	ds_write_b128 v208, v[128:131] offset:16
	ds_read_b128 v[216:219], v210
	ds_read_b128 v[220:223], v210 offset:1152
	s_waitcnt lgkmcnt(0)
	global_store_dwordx4 v236, v[216:219], s[6:7]
	global_store_dwordx4 v236, v[220:223], s[100:101]
	s_cbranch_vccnz .LBB0_325
	v_mov_b32_e32 v196, v133
	v_mov_b32_e32 v197, v129
	v_mov_b32_e32 v194, v132
	v_mov_b32_e32 v195, v128
	v_pk_mul_f32 v[196:197], v[196:197], v[196:197]
	v_mov_b32_e32 v198, v135
	v_mov_b32_e32 v199, v131
	v_pk_fma_f32 v[194:195], v[194:195], v[194:195], v[196:197]
	v_mov_b32_e32 v196, v134
	v_mov_b32_e32 v197, v130
	v_pk_mul_f32 v[198:199], v[198:199], v[198:199]
	s_nop 0
	v_pk_fma_f32 v[196:197], v[196:197], v[196:197], v[198:199]
	s_nop 0
	v_pk_add_f32 v[194:195], v[194:195], v[196:197]
	s_nop 0
	v_add_f32_e32 v251, v194, v195
	ds_read_b128 v[194:197], v192
	ds_read_b128 v[198:201], v192 offset:16
	s_waitcnt lgkmcnt(1)
	v_pk_mul_f32 v[134:135], v[134:135], v[196:197]
	v_pk_mul_f32 v[132:133], v[132:133], v[194:195]
	s_waitcnt lgkmcnt(0)
	v_pk_mul_f32 v[194:195], v[130:131], v[200:201]
	v_pk_mul_f32 v[130:131], v[128:129], v[198:199]
	v_cvt_pk_bf16_f32 v128, v132, v133
	v_cvt_pk_bf16_f32 v129, v134, v135
	v_cvt_pk_bf16_f32 v130, v130, v131
	v_cvt_pk_bf16_f32 v131, v194, v195
	ds_bpermute_b32 v128, v206, v128
	ds_bpermute_b32 v129, v206, v129
	ds_bpermute_b32 v130, v206, v130
	ds_bpermute_b32 v131, v206, v131
	s_waitcnt lgkmcnt(0)
	global_store_dwordx4 v[238:239], v[128:131], off
.LBB0_325:
	ds_read_b128 v[132:135], v249 offset:512
	ds_read_b128 v[128:131], v249 offset:528
	s_lshl_b32 s76, s76, 2
	v_cmp_eq_u32_e64 s[44:45], 0, v250
	s_ashr_i32 s77, s76, 31
	s_waitcnt lgkmcnt(1)
	v_pk_fma_f32 v[126:127], v[126:127], v[134:135], v[190:191]
	v_pk_fma_f32 v[124:125], v[124:125], v[132:133], v[188:189]
	s_waitcnt lgkmcnt(0)
	v_pk_fma_f32 v[122:123], v[122:123], v[130:131], v[186:187]
	v_pk_fma_f32 v[120:121], v[120:121], v[128:129], v[184:185]
	s_and_b64 vcc, exec, s[46:47]
	ds_write_b128 v208, v[124:127]
	ds_write_b128 v208, v[120:123] offset:16
	ds_read_b128 v[216:219], v210
	ds_read_b128 v[220:223], v210 offset:1152
	s_waitcnt lgkmcnt(0)
	global_store_dwordx4 v236, v[216:219], s[6:7] offset:512
	global_store_dwordx4 v236, v[220:223], s[100:101] offset:512
	s_cbranch_vccnz .LBB0_329
	ds_read_b128 v[184:187], v192 offset:512
	ds_read_b128 v[188:191], v192 offset:528
	s_waitcnt lgkmcnt(1)
	v_pk_mul_f32 v[184:185], v[124:125], v[184:185]
	s_waitcnt lgkmcnt(0)
	v_pk_mul_f32 v[188:189], v[120:121], v[188:189]
	v_mul_f32_e32 v121, v121, v121
	v_mul_f32_e32 v125, v125, v125
	v_fmac_f32_e32 v121, v120, v120
	v_mul_f32_e32 v120, v123, v123
	v_pk_mul_f32 v[190:191], v[122:123], v[190:191]
	v_fmac_f32_e32 v125, v124, v124
	v_mul_f32_e32 v124, v127, v127
	v_fmac_f32_e32 v120, v122, v122
	v_and_b32_e32 v122, 64, v242
	v_fmac_f32_e32 v124, v126, v126
	v_add_f32_e32 v120, v121, v120
	v_xor_b32_e32 v121, 16, v242
	v_add_u32_e32 v122, 64, v122
	v_add_f32_e32 v124, v125, v124
	v_cmp_lt_i32_e32 vcc, v121, v122
	v_add_f32_e32 v120, v124, v120
	v_add_f32_e32 v120, v251, v120
	v_cndmask_b32_e32 v121, v242, v121, vcc
	v_lshlrev_b32_e32 v121, 2, v121
	ds_bpermute_b32 v121, v121, v120
	v_pk_mul_f32 v[186:187], v[126:127], v[186:187]
	v_cvt_pk_bf16_f32 v184, v184, v185
	v_cvt_pk_bf16_f32 v185, v186, v187
	v_cvt_pk_bf16_f32 v186, v188, v189
	s_waitcnt lgkmcnt(0)
	v_add_f32_e32 v120, v120, v121
	v_xor_b32_e32 v121, 32, v242
	v_cmp_lt_i32_e32 vcc, v121, v122
	v_cvt_pk_bf16_f32 v187, v190, v191
	ds_bpermute_b32 v184, v206, v184
	ds_bpermute_b32 v185, v206, v185
	ds_bpermute_b32 v186, v206, v186
	ds_bpermute_b32 v187, v206, v187
	s_waitcnt lgkmcnt(0)
	global_store_dwordx4 v[238:239], v[184:187], off offset:256
	v_cndmask_b32_e32 v121, v242, v121, vcc
	v_lshlrev_b32_e32 v121, 2, v121
	ds_bpermute_b32 v121, v121, v120
	s_and_saveexec_b64 s[54:55], s[44:45]
	s_cbranch_execz .LBB0_328
	v_lshlrev_b64 v[122:123], 6, v[226:227]
	v_lshl_add_u64 v[122:123], s[20:21], 0, v[122:123]
	v_lshl_add_u64 v[122:123], s[76:77], 2, v[122:123]
	s_lshl_b32 s92, s91, 2
	v_lshl_add_u64 v[122:123], v[122:123], 0, s[92:93]
	s_waitcnt lgkmcnt(0)
	v_add_f32_e32 v120, v120, v121
	global_store_dword v[122:123], v120, off

; #define LAS __attribute__((address_space(3)))
; __device__ __forceinline__ unsigned cvt_pk_bf16(float lo, float hi) { const cvt_f32x2_t v = {lo, hi}; const cvt_bf16x2_t b = __builtin_convertvector(v, cvt_bf16x2_t); return __builtin_bit_cast(unsigned, b); }
; __device__ __forceinline__ float sq4(f32x4 v) { return (v[0] * v[0] + v[1] * v[1]) + (v[2] * v[2] + v[3] * v[3]); }
;     __device__ __forceinline__ void operator()(const f32x4 (&acc)[2][2][4][2], const Unit& u, int wr, int wc, int fr, int fq) const {
;     ...
;             for (int m = 0; m < 4; ++m) {
;                 const int row = u.pm * 256 + ai * 128 + wr * 64 + m * 16 + fr;
;                 const size_t off = (size_t)row * DM + col0;
;                 float ss = 0.f;
; #pragma unroll
;                 for (int bj = 0; bj < 2; ++bj) {
;                     const f32x4 xo0 = xr[m][bj][0] + *(const LAS f32x4*)(gtp + 128 * bj) * acc[ai][bj][m][0], xo1 = xr[m][bj][1] + *(const LAS f32x4*)(gtp + 128 * bj + 4) * acc[ai][bj][m][1];
;                     *(f32x4*)(xout + off + 128 * bj) = xo0; *(f32x4*)(xout + off + 128 * bj + 4) = xo1;
;                     if (gmn) { ss += sq4(xo0) + sq4(xo1); const f32x4 a = xo0 * *(const LAS f32x4*)(gmp + 128 * bj), c = xo1 * *(const LAS f32x4*)(gmp + 128 * bj + 4);
;                         u32x4 w; w.x = cvt_pk_bf16(a[0], a[1]); w.y = cvt_pk_bf16(a[2], a[3]); w.z = cvt_pk_bf16(c[0], c[1]); w.w = cvt_pk_bf16(c[2], c[3]); *(u32x4*)(AX + off + 128 * bj) = w; }
;                 }
;                 if (gmn) { ss += __shfl_xor(ss, 16); ss += __shfl_xor(ss, 32); if (fq == 0) statx[(size_t)row * 16 + u.pn * 4 + wc] = ss; }
.LBB0_329:
	s_waitcnt lgkmcnt(0)
	v_lshlrev_b64 v[120:121], 10, v[234:235]
	v_lshl_add_u64 v[184:185], v[120:121], 0, v[224:225]
	v_pk_fma_f32 v[120:121], v[118:119], v[150:151], v[182:183]
	v_pk_fma_f32 v[118:119], v[116:117], v[148:149], v[180:181]
	v_pk_fma_f32 v[124:125], v[110:111], v[142:143], v[178:179]
	v_pk_fma_f32 v[122:123], v[108:109], v[140:141], v[176:177]
	v_lshl_add_u64 v[126:127], v[184:185], 2, s[6:7]
	v_lshl_add_u32 v126, v184, 2, v246
	s_mov_b64 s[54:55], -1
	s_and_b64 vcc, exec, s[46:47]
	v_pk_fma_f32 v[116:117], v[100:101], v[132:133], v[172:173]
	v_pk_fma_f32 v[108:109], v[92:93], v[128:129], v[168:169]
	ds_write_b128 v208, v[118:121]
	ds_write_b128 v208, v[122:125] offset:16
	ds_read_b128 v[216:219], v210
	ds_read_b128 v[220:223], v210 offset:1152
	s_waitcnt lgkmcnt(0)
	global_store_dwordx4 v126, v[216:219], s[6:7]
	global_store_dwordx4 v126, v[220:223], s[100:101]
	s_cbranch_vccnz .LBB0_333
	v_mul_f32_e32 v92, v119, v119
	v_mul_f32_e32 v93, v121, v121
	ds_read_b128 v[176:179], v192
	ds_read_b128 v[180:183], v192 offset:16
	v_fmac_f32_e32 v92, v118, v118
	v_fmac_f32_e32 v93, v120, v120
	v_add_f32_e32 v92, v92, v93
	v_mul_f32_e32 v93, v123, v123
	v_mul_f32_e32 v100, v125, v125
	v_fmac_f32_e32 v93, v122, v122
	v_fmac_f32_e32 v100, v124, v124
	v_add_f32_e32 v93, v93, v100
	v_add_f32_e32 v172, v92, v93
	s_waitcnt lgkmcnt(1)
	v_pk_mul_f32 v[92:93], v[120:121], v[178:179]
	v_pk_mul_f32 v[100:101], v[118:119], v[176:177]
	s_waitcnt lgkmcnt(0)
	v_pk_mul_f32 v[110:111], v[124:125], v[182:183]
	v_pk_mul_f32 v[120:121], v[122:123], v[180:181]
	v_cvt_pk_bf16_f32 v118, v100, v101
	v_cvt_pk_bf16_f32 v119, v92, v93
	v_cvt_pk_bf16_f32 v120, v120, v121
	v_cvt_pk_bf16_f32 v121, v110, v111
	v_lshl_add_u64 v[92:93], v[184:185], 1, s[16:17]
	ds_bpermute_b32 v118, v206, v118
	ds_bpermute_b32 v119, v206, v119
	ds_bpermute_b32 v120, v206, v120
	ds_bpermute_b32 v121, v206, v121
	s_waitcnt lgkmcnt(0)
	v_lshl_add_u64 v[92:93], v[204:205], 0, v[92:93]
	global_store_dwordx4 v[92:93], v[118:121], off
	v_pk_fma_f32 v[110:111], v[94:95], v[130:131], v[170:171]
	s_nop 0
	v_pk_fma_f32 v[118:119], v[102:103], v[134:135], v[174:175]
	ds_write_b128 v208, v[116:119]
	ds_write_b128 v208, v[108:111] offset:16
	ds_read_b128 v[216:219], v210
	ds_read_b128 v[220:223], v210 offset:1152
	ds_read_b128 v[120:123], v192 offset:512
	s_waitcnt lgkmcnt(0)
	v_pk_mul_f32 v[100:101], v[118:119], v[122:123]
	v_pk_mul_f32 v[124:125], v[116:117], v[120:121]
	ds_read_b128 v[120:123], v192 offset:528
	s_waitcnt lgkmcnt(0)
	v_pk_mul_f32 v[168:169], v[110:111], v[122:123]
	v_pk_mul_f32 v[122:123], v[108:109], v[120:121]
	v_cvt_pk_bf16_f32 v120, v124, v125
	v_cvt_pk_bf16_f32 v121, v100, v101
	s_waitcnt lgkmcnt(0)
	global_store_dwordx4 v126, v[216:219], s[6:7] offset:512
	global_store_dwordx4 v126, v[220:223], s[100:101] offset:512
	v_cvt_pk_bf16_f32 v122, v122, v123
	v_cvt_pk_bf16_f32 v123, v168, v169
	ds_bpermute_b32 v120, v206, v120
	ds_bpermute_b32 v121, v206, v121
	ds_bpermute_b32 v122, v206, v122
	ds_bpermute_b32 v123, v206, v123
	s_waitcnt lgkmcnt(0)
	global_store_dwordx4 v[92:93], v[120:123], off offset:256
	v_mul_f32_e32 v92, v117, v117
	v_mul_f32_e32 v93, v119, v119
	v_fmac_f32_e32 v92, v116, v116
	v_fmac_f32_e32 v93, v118, v118
	v_add_f32_e32 v92, v92, v93
	v_mul_f32_e32 v93, v109, v109
	v_mul_f32_e32 v100, v111, v111
	v_fmac_f32_e32 v93, v108, v108
	v_fmac_f32_e32 v100, v110, v110
	v_add_f32_e32 v93, v93, v100
	v_and_b32_e32 v100, 64, v242
	v_add_f32_e32 v92, v92, v93
	v_xor_b32_e32 v93, 16, v242
	v_add_u32_e32 v100, 64, v100
	v_cmp_lt_i32_e32 vcc, v93, v100
	v_add_f32_e32 v92, v172, v92
	s_nop 0
	v_cndmask_b32_e32 v93, v242, v93, vcc
	v_lshlrev_b32_e32 v93, 2, v93
	ds_bpermute_b32 v93, v93, v92
	s_waitcnt lgkmcnt(0)
	v_add_f32_e32 v92, v92, v93
	v_xor_b32_e32 v93, 32, v242
	v_cmp_lt_i32_e32 vcc, v93, v100
	s_nop 1
	v_cndmask_b32_e32 v93, v242, v93, vcc
	v_lshlrev_b32_e32 v93, 2, v93
	ds_bpermute_b32 v93, v93, v92
	s_and_saveexec_b64 s[54:55], s[44:45]
	s_cbranch_execz .LBB0_332
	v_lshlrev_b64 v[100:101], 6, v[234:235]
	v_lshl_add_u64 v[100:101], s[20:21], 0, v[100:101]
	v_lshl_add_u64 v[100:101], s[76:77], 2, v[100:101]
	s_lshl_b32 s92, s91, 2
	v_lshl_add_u64 v[100:101], v[100:101], 0, s[92:93]
	s_waitcnt lgkmcnt(0)
	v_add_f32_e32 v92, v92, v93
	global_store_dword v[100:101], v92, off

; #define LAS __attribute__((address_space(3)))
; __device__ __forceinline__ unsigned cvt_pk_bf16(float lo, float hi) { const cvt_f32x2_t v = {lo, hi}; const cvt_bf16x2_t b = __builtin_convertvector(v, cvt_bf16x2_t); return __builtin_bit_cast(unsigned, b); }
; __device__ __forceinline__ float sq4(f32x4 v) { return (v[0] * v[0] + v[1] * v[1]) + (v[2] * v[2] + v[3] * v[3]); }
;     __device__ __forceinline__ void operator()(const f32x4 (&acc)[2][2][4][2], const Unit& u, int wr, int wc, int fr, int fq) const {
;     ...
;             for (int m = 0; m < 4; ++m) {
;                 const int row = u.pm * 256 + ai * 128 + wr * 64 + m * 16 + fr;
;                 const size_t off = (size_t)row * DM + col0;
;                 float ss = 0.f;
; #pragma unroll
;                 for (int bj = 0; bj < 2; ++bj) {
;                     const f32x4 xo0 = xr[m][bj][0] + *(const LAS f32x4*)(gtp + 128 * bj) * acc[ai][bj][m][0], xo1 = xr[m][bj][1] + *(const LAS f32x4*)(gtp + 128 * bj + 4) * acc[ai][bj][m][1];
;                     *(f32x4*)(xout + off + 128 * bj) = xo0; *(f32x4*)(xout + off + 128 * bj + 4) = xo1;
;                     if (gmn) { ss += sq4(xo0) + sq4(xo1); const f32x4 a = xo0 * *(const LAS f32x4*)(gmp + 128 * bj), c = xo1 * *(const LAS f32x4*)(gmp + 128 * bj + 4);
;                         u32x4 w; w.x = cvt_pk_bf16(a[0], a[1]); w.y = cvt_pk_bf16(a[2], a[3]); w.z = cvt_pk_bf16(c[0], c[1]); w.w = cvt_pk_bf16(c[2], c[3]); *(u32x4*)(AX + off + 128 * bj) = w; }
;                 }
;                 if (gmn) { ss += __shfl_xor(ss, 16); ss += __shfl_xor(ss, 32); if (fq == 0) statx[(size_t)row * 16 + u.pn * 4 + wc] = ss; }
.LBB0_333:
	s_andn2_b64 vcc, exec, s[54:55]
	s_cbranch_vccnz .LBB0_335
	v_pk_fma_f32 v[118:119], v[102:103], v[134:135], v[174:175]
	v_pk_fma_f32 v[110:111], v[94:95], v[130:131], v[170:171]
	ds_write_b128 v208, v[116:119]
	ds_write_b128 v208, v[108:111] offset:16
	ds_read_b128 v[216:219], v210
	ds_read_b128 v[220:223], v210 offset:1152
	s_waitcnt lgkmcnt(0)
	global_store_dwordx4 v126, v[216:219], s[6:7] offset:512
	global_store_dwordx4 v126, v[220:223], s[100:101] offset:512
.LBB0_335:
	s_waitcnt lgkmcnt(0)
	v_lshlrev_b64 v[92:93], 10, v[232:233]
	v_lshl_add_u64 v[94:95], v[92:93], 0, v[224:225]
	v_pk_fma_f32 v[98:99], v[98:99], v[150:151], v[166:167]
	v_pk_fma_f32 v[96:97], v[96:97], v[148:149], v[164:165]
	v_pk_fma_f32 v[102:103], v[90:91], v[142:143], v[162:163]
	v_pk_fma_f32 v[100:101], v[88:89], v[140:141], v[160:161]
	v_lshl_add_u64 v[108:109], v[94:95], 2, s[6:7]
	v_lshl_add_u32 v108, v94, 2, v246
	s_mov_b64 s[54:55], -1
	s_and_b64 vcc, exec, s[46:47]
	v_pk_fma_f32 v[92:93], v[84:85], v[132:133], v[156:157]
	v_pk_fma_f32 v[88:89], v[76:77], v[128:129], v[152:153]
	ds_write_b128 v208, v[96:99]
	ds_write_b128 v208, v[100:103] offset:16
	ds_read_b128 v[216:219], v210
	ds_read_b128 v[220:223], v210 offset:1152
	s_waitcnt lgkmcnt(0)
	global_store_dwordx4 v108, v[216:219], s[6:7]
	global_store_dwordx4 v108, v[220:223], s[100:101]
	s_cbranch_vccnz .LBB0_339
	v_mul_f32_e32 v76, v97, v97
	v_mul_f32_e32 v77, v99, v99
	ds_read_b128 v[116:119], v192
	ds_read_b128 v[120:123], v192 offset:16
	v_fmac_f32_e32 v76, v96, v96
	v_fmac_f32_e32 v77, v98, v98
	v_add_f32_e32 v76, v76, v77
	v_mul_f32_e32 v77, v101, v101
	v_mul_f32_e32 v84, v103, v103
	v_fmac_f32_e32 v77, v100, v100
	v_fmac_f32_e32 v84, v102, v102
	v_add_f32_e32 v77, v77, v84
	v_add_f32_e32 v110, v76, v77
	s_waitcnt lgkmcnt(1)
	v_pk_mul_f32 v[76:77], v[98:99], v[118:119]
	v_pk_mul_f32 v[84:85], v[96:97], v[116:117]
	s_waitcnt lgkmcnt(0)
	v_pk_mul_f32 v[90:91], v[102:103], v[122:123]
	v_pk_mul_f32 v[98:99], v[100:101], v[120:121]
	v_cvt_pk_bf16_f32 v96, v84, v85
	v_cvt_pk_bf16_f32 v97, v76, v77
	v_cvt_pk_bf16_f32 v98, v98, v99
	v_cvt_pk_bf16_f32 v99, v90, v91
	v_lshl_add_u64 v[76:77], v[94:95], 1, s[16:17]
	v_lshl_add_u64 v[76:77], v[204:205], 0, v[76:77]
	v_pk_fma_f32 v[94:95], v[86:87], v[134:135], v[158:159]
	ds_bpermute_b32 v96, v206, v96
	ds_bpermute_b32 v97, v206, v97
	ds_bpermute_b32 v98, v206, v98
	ds_bpermute_b32 v99, v206, v99
	s_waitcnt lgkmcnt(0)
	global_store_dwordx4 v[76:77], v[96:99], off
	v_pk_fma_f32 v[90:91], v[78:79], v[130:131], v[154:155]
	ds_write_b128 v208, v[92:95]
	ds_write_b128 v208, v[88:91] offset:16
	ds_read_b128 v[216:219], v210
	ds_read_b128 v[220:223], v210 offset:1152
	ds_read_b128 v[96:99], v192 offset:512
	s_waitcnt lgkmcnt(0)
	v_pk_mul_f32 v[84:85], v[94:95], v[98:99]
	v_pk_mul_f32 v[100:101], v[92:93], v[96:97]
	ds_read_b128 v[96:99], v192 offset:528
	s_waitcnt lgkmcnt(0)
	v_pk_mul_f32 v[102:103], v[90:91], v[98:99]
	v_pk_mul_f32 v[98:99], v[88:89], v[96:97]
	v_cvt_pk_bf16_f32 v96, v100, v101
	v_cvt_pk_bf16_f32 v97, v84, v85
	s_waitcnt lgkmcnt(0)
	global_store_dwordx4 v108, v[216:219], s[6:7] offset:512
	global_store_dwordx4 v108, v[220:223], s[100:101] offset:512
	v_cvt_pk_bf16_f32 v98, v98, v99
	v_cvt_pk_bf16_f32 v99, v102, v103
	ds_bpermute_b32 v96, v206, v96
	ds_bpermute_b32 v97, v206, v97
	ds_bpermute_b32 v98, v206, v98
	ds_bpermute_b32 v99, v206, v99
	s_waitcnt lgkmcnt(0)
	global_store_dwordx4 v[76:77], v[96:99], off offset:256
	v_mul_f32_e32 v76, v93, v93
	v_mul_f32_e32 v77, v95, v95
	v_fmac_f32_e32 v76, v92, v92
	v_fmac_f32_e32 v77, v94, v94
	v_add_f32_e32 v76, v76, v77
	v_mul_f32_e32 v77, v89, v89
	v_mul_f32_e32 v84, v91, v91
	v_fmac_f32_e32 v77, v88, v88
	v_fmac_f32_e32 v84, v90, v90
	v_add_f32_e32 v77, v77, v84
	v_and_b32_e32 v84, 64, v242
	v_add_f32_e32 v76, v76, v77
	v_xor_b32_e32 v77, 16, v242
	v_add_u32_e32 v84, 64, v84
	v_cmp_lt_i32_e32 vcc, v77, v84
	v_add_f32_e32 v76, v110, v76
	s_nop 0
	v_cndmask_b32_e32 v77, v242, v77, vcc
	v_lshlrev_b32_e32 v77, 2, v77
	ds_bpermute_b32 v77, v77, v76
	s_waitcnt lgkmcnt(0)
	v_add_f32_e32 v76, v76, v77
	v_xor_b32_e32 v77, 32, v242
	v_cmp_lt_i32_e32 vcc, v77, v84
	s_nop 1
	v_cndmask_b32_e32 v77, v242, v77, vcc
	v_lshlrev_b32_e32 v77, 2, v77
	ds_bpermute_b32 v77, v77, v76
	s_and_saveexec_b64 s[54:55], s[44:45]
	s_cbranch_execz .LBB0_338
	v_lshlrev_b64 v[84:85], 6, v[232:233]
	v_lshl_add_u64 v[84:85], s[20:21], 0, v[84:85]
	v_lshl_add_u64 v[84:85], s[76:77], 2, v[84:85]
	s_lshl_b32 s92, s91, 2
	v_lshl_add_u64 v[84:85], v[84:85], 0, s[92:93]
	s_waitcnt lgkmcnt(0)
	v_add_f32_e32 v76, v76, v77
	global_store_dword v[84:85], v76, off

; #define LAS __attribute__((address_space(3)))
; __device__ __forceinline__ unsigned cvt_pk_bf16(float lo, float hi) { const cvt_f32x2_t v = {lo, hi}; const cvt_bf16x2_t b = __builtin_convertvector(v, cvt_bf16x2_t); return __builtin_bit_cast(unsigned, b); }
; __device__ __forceinline__ float sq4(f32x4 v) { return (v[0] * v[0] + v[1] * v[1]) + (v[2] * v[2] + v[3] * v[3]); }
;     __device__ __forceinline__ void operator()(const f32x4 (&acc)[2][2][4][2], const Unit& u, int wr, int wc, int fr, int fq) const {
;     ...
;             for (int m = 0; m < 4; ++m) {
;                 const int row = u.pm * 256 + ai * 128 + wr * 64 + m * 16 + fr;
;                 const size_t off = (size_t)row * DM + col0;
;                 float ss = 0.f;
; #pragma unroll
;                 for (int bj = 0; bj < 2; ++bj) {
;                     const f32x4 xo0 = xr[m][bj][0] + *(const LAS f32x4*)(gtp + 128 * bj) * acc[ai][bj][m][0], xo1 = xr[m][bj][1] + *(const LAS f32x4*)(gtp + 128 * bj + 4) * acc[ai][bj][m][1];
;                     *(f32x4*)(xout + off + 128 * bj) = xo0; *(f32x4*)(xout + off + 128 * bj + 4) = xo1;
;                     if (gmn) { ss += sq4(xo0) + sq4(xo1); const f32x4 a = xo0 * *(const LAS f32x4*)(gmp + 128 * bj), c = xo1 * *(const LAS f32x4*)(gmp + 128 * bj + 4);
;                         u32x4 w; w.x = cvt_pk_bf16(a[0], a[1]); w.y = cvt_pk_bf16(a[2], a[3]); w.z = cvt_pk_bf16(c[0], c[1]); w.w = cvt_pk_bf16(c[2], c[3]); *(u32x4*)(AX + off + 128 * bj) = w; }
;                 }
;                 if (gmn) { ss += __shfl_xor(ss, 16); ss += __shfl_xor(ss, 32); if (fq == 0) statx[(size_t)row * 16 + u.pn * 4 + wc] = ss; }
.LBB0_339:
	s_andn2_b64 vcc, exec, s[54:55]
	s_cbranch_vccnz .LBB0_341
	v_pk_fma_f32 v[94:95], v[86:87], v[134:135], v[158:159]
	v_pk_fma_f32 v[90:91], v[78:79], v[130:131], v[154:155]
	ds_write_b128 v208, v[92:95]
	ds_write_b128 v208, v[88:91] offset:16
	ds_read_b128 v[216:219], v210
	ds_read_b128 v[220:223], v210 offset:1152
	s_waitcnt lgkmcnt(0)
	global_store_dwordx4 v108, v[216:219], s[6:7] offset:512
	global_store_dwordx4 v108, v[220:223], s[100:101] offset:512
.LBB0_341:
	s_waitcnt lgkmcnt(0)
	v_lshlrev_b64 v[76:77], 10, v[230:231]
	v_lshl_add_u64 v[78:79], v[76:77], 0, v[224:225]
	v_pk_fma_f32 v[82:83], v[82:83], v[150:151], v[146:147]
	v_pk_fma_f32 v[80:81], v[80:81], v[148:149], v[144:145]
	v_pk_fma_f32 v[86:87], v[74:75], v[142:143], v[138:139]
	v_pk_fma_f32 v[84:85], v[72:73], v[140:141], v[136:137]
	v_lshl_add_u64 v[88:89], v[78:79], 2, s[6:7]
	v_lshl_add_u32 v88, v78, 2, v246
	s_mov_b64 s[54:55], -1
	s_and_b64 vcc, exec, s[46:47]
	v_pk_fma_f32 v[76:77], v[68:69], v[132:133], v[112:113]
	v_pk_fma_f32 v[72:73], v[64:65], v[128:129], v[104:105]
	ds_write_b128 v208, v[80:83]
	ds_write_b128 v208, v[84:87] offset:16
	ds_read_b128 v[216:219], v210
	ds_read_b128 v[220:223], v210 offset:1152
	s_waitcnt lgkmcnt(0)
	global_store_dwordx4 v88, v[216:219], s[6:7]
	global_store_dwordx4 v88, v[220:223], s[100:101]
	s_cbranch_vccnz .LBB0_345
	v_mul_f32_e32 v64, v81, v81
	v_mul_f32_e32 v65, v83, v83
	ds_read_b128 v[90:93], v192
	ds_read_b128 v[94:97], v192 offset:16
	v_fmac_f32_e32 v64, v80, v80
	v_fmac_f32_e32 v65, v82, v82
	v_add_f32_e32 v64, v64, v65
	v_mul_f32_e32 v65, v85, v85
	v_mul_f32_e32 v68, v87, v87
	v_fmac_f32_e32 v65, v84, v84
	v_fmac_f32_e32 v68, v86, v86
	v_add_f32_e32 v65, v65, v68
	v_add_f32_e32 v98, v64, v65
	s_waitcnt lgkmcnt(1)
	v_pk_mul_f32 v[64:65], v[82:83], v[92:93]
	v_pk_mul_f32 v[68:69], v[80:81], v[90:91]
	s_waitcnt lgkmcnt(0)
	v_pk_mul_f32 v[74:75], v[86:87], v[96:97]
	v_pk_mul_f32 v[82:83], v[84:85], v[94:95]
	v_cvt_pk_bf16_f32 v80, v68, v69
	v_cvt_pk_bf16_f32 v81, v64, v65
	v_cvt_pk_bf16_f32 v82, v82, v83
	v_cvt_pk_bf16_f32 v83, v74, v75
	v_lshl_add_u64 v[64:65], v[78:79], 1, s[16:17]
	v_lshl_add_u64 v[64:65], v[204:205], 0, v[64:65]
	v_pk_fma_f32 v[78:79], v[70:71], v[134:135], v[114:115]
	ds_bpermute_b32 v80, v206, v80
	ds_bpermute_b32 v81, v206, v81
	ds_bpermute_b32 v82, v206, v82
	ds_bpermute_b32 v83, v206, v83
	s_waitcnt lgkmcnt(0)
	global_store_dwordx4 v[64:65], v[80:83], off
	v_pk_fma_f32 v[74:75], v[66:67], v[130:131], v[106:107]
	ds_write_b128 v208, v[76:79]
	ds_write_b128 v208, v[72:75] offset:16
	ds_read_b128 v[216:219], v210
	ds_read_b128 v[220:223], v210 offset:1152
	ds_read_b128 v[80:83], v192 offset:512
	s_waitcnt lgkmcnt(0)
	v_pk_mul_f32 v[68:69], v[78:79], v[82:83]
	v_pk_mul_f32 v[84:85], v[76:77], v[80:81]
	ds_read_b128 v[80:83], v192 offset:528
	s_waitcnt lgkmcnt(0)
	v_pk_mul_f32 v[86:87], v[74:75], v[82:83]
	v_pk_mul_f32 v[82:83], v[72:73], v[80:81]
	v_cvt_pk_bf16_f32 v80, v84, v85
	v_cvt_pk_bf16_f32 v81, v68, v69
	s_waitcnt lgkmcnt(0)
	global_store_dwordx4 v88, v[216:219], s[6:7] offset:512
	global_store_dwordx4 v88, v[220:223], s[100:101] offset:512
	v_cvt_pk_bf16_f32 v82, v82, v83
	v_cvt_pk_bf16_f32 v83, v86, v87
	ds_bpermute_b32 v80, v206, v80
	ds_bpermute_b32 v81, v206, v81
	ds_bpermute_b32 v82, v206, v82
	ds_bpermute_b32 v83, v206, v83
	s_waitcnt lgkmcnt(0)
	global_store_dwordx4 v[64:65], v[80:83], off offset:256
	v_mul_f32_e32 v64, v77, v77
	v_mul_f32_e32 v65, v79, v79
	v_fmac_f32_e32 v64, v76, v76
	v_fmac_f32_e32 v65, v78, v78
	v_add_f32_e32 v64, v64, v65
	v_mul_f32_e32 v65, v73, v73
	v_mul_f32_e32 v68, v75, v75
	v_fmac_f32_e32 v65, v72, v72
	v_fmac_f32_e32 v68, v74, v74
	v_add_f32_e32 v65, v65, v68
	v_and_b32_e32 v68, 64, v242
	v_add_f32_e32 v64, v64, v65
	v_xor_b32_e32 v65, 16, v242
	v_add_u32_e32 v68, 64, v68
	v_cmp_lt_i32_e32 vcc, v65, v68
	v_add_f32_e32 v64, v98, v64
	s_nop 0
	v_cndmask_b32_e32 v65, v242, v65, vcc
	v_lshlrev_b32_e32 v65, 2, v65
	ds_bpermute_b32 v65, v65, v64
	s_waitcnt lgkmcnt(0)
	v_add_f32_e32 v64, v64, v65
	v_xor_b32_e32 v65, 32, v242
	v_cmp_lt_i32_e32 vcc, v65, v68
	s_nop 1
	v_cndmask_b32_e32 v65, v242, v65, vcc
	v_lshlrev_b32_e32 v65, 2, v65
	ds_bpermute_b32 v65, v65, v64
	s_and_saveexec_b64 s[54:55], s[44:45]
	s_cbranch_execz .LBB0_344
	v_lshlrev_b64 v[68:69], 6, v[230:231]
	v_lshl_add_u64 v[68:69], s[20:21], 0, v[68:69]
	v_lshl_add_u64 v[68:69], s[76:77], 2, v[68:69]
	s_lshl_b32 s92, s91, 2
	v_lshl_add_u64 v[68:69], v[68:69], 0, s[92:93]
	s_waitcnt lgkmcnt(0)
	v_add_f32_e32 v64, v64, v65
	global_store_dword v[68:69], v64, off

; #define LAS __attribute__((address_space(3)))
; __device__ __forceinline__ unsigned cvt_pk_bf16(float lo, float hi) { const cvt_f32x2_t v = {lo, hi}; const cvt_bf16x2_t b = __builtin_convertvector(v, cvt_bf16x2_t); return __builtin_bit_cast(unsigned, b); }
; __device__ __forceinline__ float sq4(f32x4 v) { return (v[0] * v[0] + v[1] * v[1]) + (v[2] * v[2] + v[3] * v[3]); }
;     __device__ __forceinline__ void operator()(const f32x4 (&acc)[2][2][4][2], const Unit& u, int wr, int wc, int fr, int fq) const {
;     ...
;         for (int ai = 0; ai < 2; ++ai) {
;             f32x4 xr[4][2][2];
; #pragma unroll
;             for (int m = 0; m < 4; ++m) { const size_t off = (size_t)(u.pm * 256 + ai * 128 + wr * 64 + m * 16 + fr) * DM + col0;
; #pragma unroll
;                 for (int bj = 0; bj < 2; ++bj)
; #pragma unroll
;                     for (int n = 0; n < 2; ++n) xr[m][bj][n] = *(const f32x4*)(xin + off + 128 * bj + 4 * n); }
;             asm volatile("" ::: "memory");
; #pragma unroll
;             for (int m = 0; m < 4; ++m) {
;                 const int row = u.pm * 256 + ai * 128 + wr * 64 + m * 16 + fr;
;                 const size_t off = (size_t)row * DM + col0;
;                 float ss = 0.f;
; #pragma unroll
;                 for (int bj = 0; bj < 2; ++bj) {
;                     const f32x4 xo0 = xr[m][bj][0] + *(const LAS f32x4*)(gtp + 128 * bj) * acc[ai][bj][m][0], xo1 = xr[m][bj][1] + *(const LAS f32x4*)(gtp + 128 * bj + 4) * acc[ai][bj][m][1];
;                     *(f32x4*)(xout + off + 128 * bj) = xo0; *(f32x4*)(xout + off + 128 * bj + 4) = xo1;
;                     if (gmn) { ss += sq4(xo0) + sq4(xo1); const f32x4 a = xo0 * *(const LAS f32x4*)(gmp + 128 * bj), c = xo1 * *(const LAS f32x4*)(gmp + 128 * bj + 4);
;                         u32x4 w; w.x = cvt_pk_bf16(a[0], a[1]); w.y = cvt_pk_bf16(a[2], a[3]); w.z = cvt_pk_bf16(c[0], c[1]); w.w = cvt_pk_bf16(c[2], c[3]); *(u32x4*)(AX + off + 128 * bj) = w; }
;                 }
;                 if (gmn) { ss += __shfl_xor(ss, 16); ss += __shfl_xor(ss, 32); if (fq == 0) statx[(size_t)row * 16 + u.pn * 4 + wc] = ss; }
.LBB0_345:
	s_andn2_b64 vcc, exec, s[54:55]
	s_cbranch_vccnz .LBB0_347
	v_pk_fma_f32 v[78:79], v[70:71], v[134:135], v[114:115]
	v_pk_fma_f32 v[74:75], v[66:67], v[130:131], v[106:107]
	ds_write_b128 v208, v[76:79]
	ds_write_b128 v208, v[72:75] offset:16
	ds_read_b128 v[216:219], v210
	ds_read_b128 v[220:223], v210 offset:1152
	s_waitcnt lgkmcnt(0)
	global_store_dwordx4 v88, v[216:219], s[6:7] offset:512
	global_store_dwordx4 v88, v[220:223], s[100:101] offset:512
.LBB0_347:
	v_add_u32_e32 v134, 0x80, v226
	v_ashrrev_i32_e32 v135, 31, v134
	s_waitcnt lgkmcnt(0)
	v_lshlrev_b64 v[64:65], 12, v[134:135]
	v_add_u32_e32 v132, 0x90, v226
	v_lshl_add_u64 v[64:65], v[228:229], 0, v[64:65]
	v_ashrrev_i32_e32 v133, 31, v132
	global_load_dwordx4 v[136:139], v[64:65], off offset:16
	global_load_dwordx4 v[140:143], v[64:65], off
	global_load_dwordx4 v[120:123], v[64:65], off offset:528
	global_load_dwordx4 v[124:127], v[64:65], off offset:512
	v_lshlrev_b64 v[64:65], 12, v[132:133]
	v_add_u32_e32 v130, 0xa0, v226
	v_lshl_add_u64 v[64:65], v[228:229], 0, v[64:65]
	v_ashrrev_i32_e32 v131, 31, v130
	global_load_dwordx4 v[112:115], v[64:65], off offset:16
	global_load_dwordx4 v[116:119], v[64:65], off
	global_load_dwordx4 v[104:107], v[64:65], off offset:528
	global_load_dwordx4 v[108:111], v[64:65], off offset:512
	v_lshlrev_b64 v[64:65], 12, v[130:131]
	v_add_u32_e32 v128, 0xb0, v226
	v_lshl_add_u64 v[64:65], v[228:229], 0, v[64:65]
	v_ashrrev_i32_e32 v129, 31, v128
	global_load_dwordx4 v[96:99], v[64:65], off offset:16
	global_load_dwordx4 v[100:103], v[64:65], off
	global_load_dwordx4 v[88:91], v[64:65], off offset:528
	global_load_dwordx4 v[92:95], v[64:65], off offset:512
	v_lshlrev_b64 v[64:65], 12, v[128:129]
	v_lshl_add_u64 v[68:69], v[228:229], 0, v[64:65]
	global_load_dwordx4 v[72:75], v[68:69], off offset:16
	global_load_dwordx4 v[80:83], v[68:69], off
	global_load_dwordx4 v[64:67], v[68:69], off offset:528
	s_nop 0
	global_load_dwordx4 v[68:71], v[68:69], off offset:512
	v_lshlrev_b64 v[76:77], 10, v[134:135]
	v_lshl_add_u64 v[144:145], v[76:77], 0, v[224:225]
	ds_read_b128 v[84:87], v249
	ds_read_b128 v[76:79], v249 offset:16
	s_and_b64 vcc, exec, s[46:47]
	s_waitcnt vmcnt(15) lgkmcnt(0)
	v_pk_fma_f32 v[58:59], v[58:59], v[78:79], v[138:139]
	s_waitcnt vmcnt(14)
	v_pk_fma_f32 v[62:63], v[62:63], v[86:87], v[142:143]
	v_pk_fma_f32 v[60:61], v[60:61], v[84:85], v[140:141]
	v_pk_fma_f32 v[56:57], v[56:57], v[76:77], v[136:137]
	v_lshl_add_u64 v[136:137], v[144:145], 2, s[6:7]
	v_lshl_add_u32 v136, v144, 2, v246
	v_mov_b32_e32 v140, 0
	v_lshl_add_u64 v[138:139], v[144:145], 1, s[16:17]
	v_lshl_add_u64 v[138:139], v[204:205], 0, v[138:139]
	ds_write_b128 v208, v[60:63]
	ds_write_b128 v208, v[56:59] offset:16
	ds_read_b128 v[216:219], v210
	ds_read_b128 v[220:223], v210 offset:1152
	s_waitcnt lgkmcnt(0)
	global_store_dwordx4 v136, v[216:219], s[6:7]
	global_store_dwordx4 v136, v[220:223], s[100:101]
	s_cbranch_vccnz .LBB0_349
	v_mov_b32_e32 v142, v61
	v_mov_b32_e32 v143, v57
	v_mov_b32_e32 v140, v60
	v_mov_b32_e32 v141, v56
	v_pk_mul_f32 v[142:143], v[142:143], v[142:143]
	v_mov_b32_e32 v144, v63
	v_mov_b32_e32 v145, v59
	v_pk_fma_f32 v[140:141], v[140:141], v[140:141], v[142:143]
	v_mov_b32_e32 v142, v62
	v_mov_b32_e32 v143, v58
	v_pk_mul_f32 v[144:145], v[144:145], v[144:145]
	s_nop 0
	v_pk_fma_f32 v[142:143], v[142:143], v[142:143], v[144:145]
	s_nop 0
	v_pk_add_f32 v[140:141], v[140:141], v[142:143]
	ds_read_b128 v[142:145], v192
	ds_read_b128 v[146:149], v192 offset:16
	v_add_f32_e32 v140, v140, v141
	s_waitcnt lgkmcnt(1)
	v_pk_mul_f32 v[62:63], v[62:63], v[144:145]
	v_pk_mul_f32 v[60:61], v[60:61], v[142:143]
	s_waitcnt lgkmcnt(0)
	v_pk_mul_f32 v[142:143], v[58:59], v[148:149]
	v_pk_mul_f32 v[58:59], v[56:57], v[146:147]
	v_cvt_pk_bf16_f32 v56, v60, v61
	v_cvt_pk_bf16_f32 v57, v62, v63
	v_cvt_pk_bf16_f32 v58, v58, v59
	v_cvt_pk_bf16_f32 v59, v142, v143
	ds_bpermute_b32 v56, v206, v56
	ds_bpermute_b32 v57, v206, v57
	ds_bpermute_b32 v58, v206, v58
	ds_bpermute_b32 v59, v206, v59
	s_waitcnt lgkmcnt(0)
	global_store_dwordx4 v[138:139], v[56:59], off
.LBB0_349:
	ds_read_b128 v[60:63], v249 offset:512
	ds_read_b128 v[56:59], v249 offset:528
	s_and_b64 vcc, exec, s[46:47]
	s_waitcnt vmcnt(14) lgkmcnt(1)
	v_pk_fma_f32 v[54:55], v[54:55], v[62:63], v[126:127]
	v_pk_fma_f32 v[52:53], v[52:53], v[60:61], v[124:125]
	s_waitcnt lgkmcnt(0)
	v_pk_fma_f32 v[50:51], v[50:51], v[58:59], v[122:123]
	v_pk_fma_f32 v[48:49], v[48:49], v[56:57], v[120:121]
	ds_write_b128 v208, v[52:55]
	ds_write_b128 v208, v[48:51] offset:16
	ds_read_b128 v[216:219], v210
	ds_read_b128 v[220:223], v210 offset:1152
	s_waitcnt lgkmcnt(0)
	global_store_dwordx4 v136, v[216:219], s[6:7] offset:512
	global_store_dwordx4 v136, v[220:223], s[100:101] offset:512
	s_cbranch_vccnz .LBB0_353
	ds_read_b128 v[120:123], v192 offset:512
	ds_read_b128 v[124:127], v192 offset:528
	s_waitcnt lgkmcnt(1)
	v_pk_mul_f32 v[120:121], v[52:53], v[120:121]
	s_waitcnt lgkmcnt(0)
	v_pk_mul_f32 v[124:125], v[48:49], v[124:125]
	v_mul_f32_e32 v49, v49, v49
	v_mul_f32_e32 v53, v53, v53
	v_fmac_f32_e32 v49, v48, v48
	v_mul_f32_e32 v48, v51, v51
	v_pk_mul_f32 v[126:127], v[50:51], v[126:127]
	v_fmac_f32_e32 v53, v52, v52
	v_mul_f32_e32 v52, v55, v55
	v_fmac_f32_e32 v48, v50, v50
	v_and_b32_e32 v50, 64, v242
	v_fmac_f32_e32 v52, v54, v54
	v_add_f32_e32 v48, v49, v48
	v_xor_b32_e32 v49, 16, v242
	v_add_u32_e32 v50, 64, v50
	v_add_f32_e32 v52, v53, v52
	v_cmp_lt_i32_e32 vcc, v49, v50
	v_add_f32_e32 v48, v52, v48
	v_add_f32_e32 v48, v140, v48
	v_cndmask_b32_e32 v49, v242, v49, vcc
	v_lshlrev_b32_e32 v49, 2, v49
	ds_bpermute_b32 v49, v49, v48
	v_pk_mul_f32 v[122:123], v[54:55], v[122:123]
	v_cvt_pk_bf16_f32 v120, v120, v121
	v_cvt_pk_bf16_f32 v121, v122, v123
	v_cvt_pk_bf16_f32 v122, v124, v125
	s_waitcnt lgkmcnt(0)
	v_add_f32_e32 v48, v48, v49
	v_xor_b32_e32 v49, 32, v242
	v_cmp_lt_i32_e32 vcc, v49, v50
	v_cvt_pk_bf16_f32 v123, v126, v127
	ds_bpermute_b32 v120, v206, v120
	ds_bpermute_b32 v121, v206, v121
	ds_bpermute_b32 v122, v206, v122
	ds_bpermute_b32 v123, v206, v123
	s_waitcnt lgkmcnt(0)
	global_store_dwordx4 v[138:139], v[120:123], off offset:256
	v_cndmask_b32_e32 v49, v242, v49, vcc
	v_lshlrev_b32_e32 v49, 2, v49
	ds_bpermute_b32 v49, v49, v48
	s_and_saveexec_b64 s[54:55], s[44:45]
	s_cbranch_execz .LBB0_352
	v_lshlrev_b64 v[50:51], 6, v[134:135]
	v_lshl_add_u64 v[50:51], s[20:21], 0, v[50:51]
	v_lshl_add_u64 v[50:51], s[76:77], 2, v[50:51]
	s_lshl_b32 s92, s91, 2
	v_lshl_add_u64 v[50:51], v[50:51], 0, s[92:93]
	s_waitcnt lgkmcnt(0)
	v_add_f32_e32 v48, v48, v49
	global_store_dword v[50:51], v48, off

; #define LAS __attribute__((address_space(3)))
; __device__ __forceinline__ unsigned cvt_pk_bf16(float lo, float hi) { const cvt_f32x2_t v = {lo, hi}; const cvt_bf16x2_t b = __builtin_convertvector(v, cvt_bf16x2_t); return __builtin_bit_cast(unsigned, b); }
; __device__ __forceinline__ float sq4(f32x4 v) { return (v[0] * v[0] + v[1] * v[1]) + (v[2] * v[2] + v[3] * v[3]); }
;     __device__ __forceinline__ void operator()(const f32x4 (&acc)[2][2][4][2], const Unit& u, int wr, int wc, int fr, int fq) const {
;     ...
;             for (int m = 0; m < 4; ++m) {
;                 const int row = u.pm * 256 + ai * 128 + wr * 64 + m * 16 + fr;
;                 const size_t off = (size_t)row * DM + col0;
;                 float ss = 0.f;
; #pragma unroll
;                 for (int bj = 0; bj < 2; ++bj) {
;                     const f32x4 xo0 = xr[m][bj][0] + *(const LAS f32x4*)(gtp + 128 * bj) * acc[ai][bj][m][0], xo1 = xr[m][bj][1] + *(const LAS f32x4*)(gtp + 128 * bj + 4) * acc[ai][bj][m][1];
;                     *(f32x4*)(xout + off + 128 * bj) = xo0; *(f32x4*)(xout + off + 128 * bj + 4) = xo1;
;                     if (gmn) { ss += sq4(xo0) + sq4(xo1); const f32x4 a = xo0 * *(const LAS f32x4*)(gmp + 128 * bj), c = xo1 * *(const LAS f32x4*)(gmp + 128 * bj + 4);
;                         u32x4 w; w.x = cvt_pk_bf16(a[0], a[1]); w.y = cvt_pk_bf16(a[2], a[3]); w.z = cvt_pk_bf16(c[0], c[1]); w.w = cvt_pk_bf16(c[2], c[3]); *(u32x4*)(AX + off + 128 * bj) = w; }
;                 }
;                 if (gmn) { ss += __shfl_xor(ss, 16); ss += __shfl_xor(ss, 32); if (fq == 0) statx[(size_t)row * 16 + u.pn * 4 + wc] = ss; }
.LBB0_353:
	s_waitcnt lgkmcnt(0)
	v_lshlrev_b64 v[48:49], 10, v[132:133]
	v_lshl_add_u64 v[120:121], v[48:49], 0, v[224:225]
	s_waitcnt vmcnt(14)
	v_pk_fma_f32 v[48:49], v[46:47], v[86:87], v[118:119]
	v_pk_fma_f32 v[46:47], v[44:45], v[84:85], v[116:117]
	v_pk_fma_f32 v[52:53], v[42:43], v[78:79], v[114:115]
	v_pk_fma_f32 v[50:51], v[40:41], v[76:77], v[112:113]
	v_lshl_add_u64 v[54:55], v[120:121], 2, s[6:7]
	v_lshl_add_u32 v54, v120, 2, v246
	s_mov_b64 s[54:55], -1
	s_and_b64 vcc, exec, s[46:47]
	s_waitcnt vmcnt(12)
	v_pk_fma_f32 v[44:45], v[36:37], v[60:61], v[108:109]
	v_pk_fma_f32 v[40:41], v[28:29], v[56:57], v[104:105]
	ds_write_b128 v208, v[46:49]
	ds_write_b128 v208, v[50:53] offset:16
	ds_read_b128 v[216:219], v210
	ds_read_b128 v[220:223], v210 offset:1152
	s_waitcnt lgkmcnt(0)
	global_store_dwordx4 v54, v[216:219], s[6:7]
	global_store_dwordx4 v54, v[220:223], s[100:101]
	s_cbranch_vccnz .LBB0_357
	v_mul_f32_e32 v28, v47, v47
	v_mul_f32_e32 v29, v49, v49
	ds_read_b128 v[112:115], v192
	ds_read_b128 v[116:119], v192 offset:16
	v_fmac_f32_e32 v28, v46, v46
	v_fmac_f32_e32 v29, v48, v48
	v_add_f32_e32 v28, v28, v29
	v_mul_f32_e32 v29, v51, v51
	v_mul_f32_e32 v36, v53, v53
	v_fmac_f32_e32 v29, v50, v50
	v_fmac_f32_e32 v36, v52, v52
	v_add_f32_e32 v29, v29, v36
	v_add_f32_e32 v108, v28, v29
	s_waitcnt lgkmcnt(1)
	v_pk_mul_f32 v[28:29], v[48:49], v[114:115]
	v_pk_mul_f32 v[36:37], v[46:47], v[112:113]
	s_waitcnt lgkmcnt(0)
	v_pk_mul_f32 v[42:43], v[52:53], v[118:119]
	v_pk_mul_f32 v[48:49], v[50:51], v[116:117]
	v_cvt_pk_bf16_f32 v46, v36, v37
	v_cvt_pk_bf16_f32 v47, v28, v29
	v_cvt_pk_bf16_f32 v48, v48, v49
	v_cvt_pk_bf16_f32 v49, v42, v43
	v_lshl_add_u64 v[28:29], v[120:121], 1, s[16:17]
	ds_bpermute_b32 v46, v206, v46
	ds_bpermute_b32 v47, v206, v47
	ds_bpermute_b32 v48, v206, v48
	ds_bpermute_b32 v49, v206, v49
	s_waitcnt lgkmcnt(0)
	v_lshl_add_u64 v[28:29], v[204:205], 0, v[28:29]
	global_store_dwordx4 v[28:29], v[46:49], off
	v_pk_fma_f32 v[42:43], v[30:31], v[58:59], v[106:107]
	s_nop 0
	v_pk_fma_f32 v[46:47], v[38:39], v[62:63], v[110:111]
	ds_write_b128 v208, v[44:47]
	ds_write_b128 v208, v[40:43] offset:16
	ds_read_b128 v[216:219], v210
	ds_read_b128 v[220:223], v210 offset:1152
	ds_read_b128 v[48:51], v192 offset:512
	s_waitcnt lgkmcnt(0)
	v_pk_mul_f32 v[36:37], v[46:47], v[50:51]
	v_pk_mul_f32 v[52:53], v[44:45], v[48:49]
	ds_read_b128 v[48:51], v192 offset:528
	s_waitcnt lgkmcnt(0)
	v_pk_mul_f32 v[104:105], v[42:43], v[50:51]
	v_pk_mul_f32 v[50:51], v[40:41], v[48:49]
	v_cvt_pk_bf16_f32 v48, v52, v53
	v_cvt_pk_bf16_f32 v49, v36, v37
	s_waitcnt lgkmcnt(0)
	global_store_dwordx4 v54, v[216:219], s[6:7] offset:512
	global_store_dwordx4 v54, v[220:223], s[100:101] offset:512
	v_cvt_pk_bf16_f32 v50, v50, v51
	v_cvt_pk_bf16_f32 v51, v104, v105
	ds_bpermute_b32 v48, v206, v48
	ds_bpermute_b32 v49, v206, v49
	ds_bpermute_b32 v50, v206, v50
	ds_bpermute_b32 v51, v206, v51
	s_waitcnt lgkmcnt(0)
	global_store_dwordx4 v[28:29], v[48:51], off offset:256
	v_mul_f32_e32 v28, v45, v45
	v_mul_f32_e32 v29, v47, v47
	v_fmac_f32_e32 v28, v44, v44
	v_fmac_f32_e32 v29, v46, v46
	v_add_f32_e32 v28, v28, v29
	v_mul_f32_e32 v29, v41, v41
	v_mul_f32_e32 v36, v43, v43
	v_fmac_f32_e32 v29, v40, v40
	v_fmac_f32_e32 v36, v42, v42
	v_add_f32_e32 v29, v29, v36
	v_and_b32_e32 v36, 64, v242
	v_add_f32_e32 v28, v28, v29
	v_xor_b32_e32 v29, 16, v242
	v_add_u32_e32 v36, 64, v36
	v_cmp_lt_i32_e32 vcc, v29, v36
	v_add_f32_e32 v28, v108, v28
	s_nop 0
	v_cndmask_b32_e32 v29, v242, v29, vcc
	v_lshlrev_b32_e32 v29, 2, v29
	ds_bpermute_b32 v29, v29, v28
	s_waitcnt lgkmcnt(0)
	v_add_f32_e32 v28, v28, v29
	v_xor_b32_e32 v29, 32, v242
	v_cmp_lt_i32_e32 vcc, v29, v36
	s_nop 1
	v_cndmask_b32_e32 v29, v242, v29, vcc
	v_lshlrev_b32_e32 v29, 2, v29
	ds_bpermute_b32 v29, v29, v28
	s_and_saveexec_b64 s[54:55], s[44:45]
	s_cbranch_execz .LBB0_356
	v_lshlrev_b64 v[36:37], 6, v[132:133]
	v_lshl_add_u64 v[36:37], s[20:21], 0, v[36:37]
	v_lshl_add_u64 v[36:37], s[76:77], 2, v[36:37]
	s_lshl_b32 s92, s91, 2
	v_lshl_add_u64 v[36:37], v[36:37], 0, s[92:93]
	s_waitcnt lgkmcnt(0)
	v_add_f32_e32 v28, v28, v29
	global_store_dword v[36:37], v28, off

; #define LAS __attribute__((address_space(3)))
; __device__ __forceinline__ unsigned cvt_pk_bf16(float lo, float hi) { const cvt_f32x2_t v = {lo, hi}; const cvt_bf16x2_t b = __builtin_convertvector(v, cvt_bf16x2_t); return __builtin_bit_cast(unsigned, b); }
; __device__ __forceinline__ float sq4(f32x4 v) { return (v[0] * v[0] + v[1] * v[1]) + (v[2] * v[2] + v[3] * v[3]); }
;     __device__ __forceinline__ void operator()(const f32x4 (&acc)[2][2][4][2], const Unit& u, int wr, int wc, int fr, int fq) const {
;     ...
;             for (int m = 0; m < 4; ++m) {
;                 const int row = u.pm * 256 + ai * 128 + wr * 64 + m * 16 + fr;
;                 const size_t off = (size_t)row * DM + col0;
;                 float ss = 0.f;
; #pragma unroll
;                 for (int bj = 0; bj < 2; ++bj) {
;                     const f32x4 xo0 = xr[m][bj][0] + *(const LAS f32x4*)(gtp + 128 * bj) * acc[ai][bj][m][0], xo1 = xr[m][bj][1] + *(const LAS f32x4*)(gtp + 128 * bj + 4) * acc[ai][bj][m][1];
;                     *(f32x4*)(xout + off + 128 * bj) = xo0; *(f32x4*)(xout + off + 128 * bj + 4) = xo1;
;                     if (gmn) { ss += sq4(xo0) + sq4(xo1); const f32x4 a = xo0 * *(const LAS f32x4*)(gmp + 128 * bj), c = xo1 * *(const LAS f32x4*)(gmp + 128 * bj + 4);
;                         u32x4 w; w.x = cvt_pk_bf16(a[0], a[1]); w.y = cvt_pk_bf16(a[2], a[3]); w.z = cvt_pk_bf16(c[0], c[1]); w.w = cvt_pk_bf16(c[2], c[3]); *(u32x4*)(AX + off + 128 * bj) = w; }
;                 }
;                 if (gmn) { ss += __shfl_xor(ss, 16); ss += __shfl_xor(ss, 32); if (fq == 0) statx[(size_t)row * 16 + u.pn * 4 + wc] = ss; }
.LBB0_357:
	s_andn2_b64 vcc, exec, s[54:55]
	s_cbranch_vccnz .LBB0_359
	v_pk_fma_f32 v[46:47], v[38:39], v[62:63], v[110:111]
	v_pk_fma_f32 v[42:43], v[30:31], v[58:59], v[106:107]
	ds_write_b128 v208, v[44:47]
	ds_write_b128 v208, v[40:43] offset:16
	ds_read_b128 v[216:219], v210
	ds_read_b128 v[220:223], v210 offset:1152
	s_waitcnt lgkmcnt(0)
	global_store_dwordx4 v54, v[216:219], s[6:7] offset:512
	global_store_dwordx4 v54, v[220:223], s[100:101] offset:512
.LBB0_359:
	s_waitcnt lgkmcnt(0)
	v_lshlrev_b64 v[28:29], 10, v[130:131]
	v_lshl_add_u64 v[30:31], v[28:29], 0, v[224:225]
	s_waitcnt vmcnt(12)
	v_pk_fma_f32 v[34:35], v[34:35], v[86:87], v[102:103]
	v_pk_fma_f32 v[32:33], v[32:33], v[84:85], v[100:101]
	v_pk_fma_f32 v[38:39], v[26:27], v[78:79], v[98:99]
	v_pk_fma_f32 v[36:37], v[24:25], v[76:77], v[96:97]
	v_lshl_add_u64 v[40:41], v[30:31], 2, s[6:7]
	v_lshl_add_u32 v40, v30, 2, v246
	s_mov_b64 s[54:55], -1
	s_and_b64 vcc, exec, s[46:47]
	s_waitcnt vmcnt(10)
	v_pk_fma_f32 v[28:29], v[20:21], v[60:61], v[92:93]
	v_pk_fma_f32 v[24:25], v[12:13], v[56:57], v[88:89]
	ds_write_b128 v208, v[32:35]
	ds_write_b128 v208, v[36:39] offset:16
	ds_read_b128 v[216:219], v210
	ds_read_b128 v[220:223], v210 offset:1152
	s_waitcnt lgkmcnt(0)
	global_store_dwordx4 v40, v[216:219], s[6:7]
	global_store_dwordx4 v40, v[220:223], s[100:101]
	s_cbranch_vccnz .LBB0_363
	v_mul_f32_e32 v12, v33, v33
	v_mul_f32_e32 v13, v35, v35
	ds_read_b128 v[42:45], v192
	ds_read_b128 v[46:49], v192 offset:16
	v_fmac_f32_e32 v12, v32, v32
	v_fmac_f32_e32 v13, v34, v34
	v_add_f32_e32 v12, v12, v13
	v_mul_f32_e32 v13, v37, v37
	v_mul_f32_e32 v20, v39, v39
	v_fmac_f32_e32 v13, v36, v36
	v_fmac_f32_e32 v20, v38, v38
	v_add_f32_e32 v13, v13, v20
	v_add_f32_e32 v50, v12, v13
	s_waitcnt lgkmcnt(1)
	v_pk_mul_f32 v[12:13], v[34:35], v[44:45]
	v_pk_mul_f32 v[20:21], v[32:33], v[42:43]
	s_waitcnt lgkmcnt(0)
	v_pk_mul_f32 v[26:27], v[38:39], v[48:49]
	v_pk_mul_f32 v[34:35], v[36:37], v[46:47]
	v_cvt_pk_bf16_f32 v32, v20, v21
	v_cvt_pk_bf16_f32 v33, v12, v13
	v_cvt_pk_bf16_f32 v34, v34, v35
	v_cvt_pk_bf16_f32 v35, v26, v27
	v_lshl_add_u64 v[12:13], v[30:31], 1, s[16:17]
	v_lshl_add_u64 v[12:13], v[204:205], 0, v[12:13]
	v_pk_fma_f32 v[30:31], v[22:23], v[62:63], v[94:95]
	ds_bpermute_b32 v32, v206, v32
	ds_bpermute_b32 v33, v206, v33
	ds_bpermute_b32 v34, v206, v34
	ds_bpermute_b32 v35, v206, v35
	s_waitcnt lgkmcnt(0)
	global_store_dwordx4 v[12:13], v[32:35], off
	v_pk_fma_f32 v[26:27], v[14:15], v[58:59], v[90:91]
	ds_write_b128 v208, v[28:31]
	ds_write_b128 v208, v[24:27] offset:16
	ds_read_b128 v[216:219], v210
	ds_read_b128 v[220:223], v210 offset:1152
	ds_read_b128 v[32:35], v192 offset:512
	s_waitcnt lgkmcnt(0)
	v_pk_mul_f32 v[20:21], v[30:31], v[34:35]
	v_pk_mul_f32 v[36:37], v[28:29], v[32:33]
	ds_read_b128 v[32:35], v192 offset:528
	s_waitcnt lgkmcnt(0)
	v_pk_mul_f32 v[38:39], v[26:27], v[34:35]
	v_pk_mul_f32 v[34:35], v[24:25], v[32:33]
	v_cvt_pk_bf16_f32 v32, v36, v37
	v_cvt_pk_bf16_f32 v33, v20, v21
	s_waitcnt lgkmcnt(0)
	global_store_dwordx4 v40, v[216:219], s[6:7] offset:512
	global_store_dwordx4 v40, v[220:223], s[100:101] offset:512
	v_cvt_pk_bf16_f32 v34, v34, v35
	v_cvt_pk_bf16_f32 v35, v38, v39
	ds_bpermute_b32 v32, v206, v32
	ds_bpermute_b32 v33, v206, v33
	ds_bpermute_b32 v34, v206, v34
	ds_bpermute_b32 v35, v206, v35
	s_waitcnt lgkmcnt(0)
	global_store_dwordx4 v[12:13], v[32:35], off offset:256
	v_mul_f32_e32 v12, v29, v29
	v_mul_f32_e32 v13, v31, v31
	v_fmac_f32_e32 v12, v28, v28
	v_fmac_f32_e32 v13, v30, v30
	v_add_f32_e32 v12, v12, v13
	v_mul_f32_e32 v13, v25, v25
	v_mul_f32_e32 v20, v27, v27
	v_fmac_f32_e32 v13, v24, v24
	v_fmac_f32_e32 v20, v26, v26
	v_add_f32_e32 v13, v13, v20
	v_and_b32_e32 v20, 64, v242
	v_add_f32_e32 v12, v12, v13
	v_xor_b32_e32 v13, 16, v242
	v_add_u32_e32 v20, 64, v20
	v_cmp_lt_i32_e32 vcc, v13, v20
	v_add_f32_e32 v12, v50, v12
	s_nop 0
	v_cndmask_b32_e32 v13, v242, v13, vcc
	v_lshlrev_b32_e32 v13, 2, v13
	ds_bpermute_b32 v13, v13, v12
	s_waitcnt lgkmcnt(0)
	v_add_f32_e32 v12, v12, v13
	v_xor_b32_e32 v13, 32, v242
	v_cmp_lt_i32_e32 vcc, v13, v20
	s_nop 1
	v_cndmask_b32_e32 v13, v242, v13, vcc
	v_lshlrev_b32_e32 v13, 2, v13
	ds_bpermute_b32 v13, v13, v12
	s_and_saveexec_b64 s[54:55], s[44:45]
	s_cbranch_execz .LBB0_362
	v_lshlrev_b64 v[20:21], 6, v[130:131]
	v_lshl_add_u64 v[20:21], s[20:21], 0, v[20:21]
	v_lshl_add_u64 v[20:21], s[76:77], 2, v[20:21]
	s_lshl_b32 s92, s91, 2
	v_lshl_add_u64 v[20:21], v[20:21], 0, s[92:93]
	s_waitcnt lgkmcnt(0)
	v_add_f32_e32 v12, v12, v13
	global_store_dword v[20:21], v12, off

; #define LAS __attribute__((address_space(3)))
;     __device__ __forceinline__ void operator()(const f32x4 (&acc)[2][2][4][2], const Unit& u, int wr, int wc, int fr, int fq) const {
;     ...
;                 for (int bj = 0; bj < 2; ++bj) {
;                     const f32x4 xo0 = xr[m][bj][0] + *(const LAS f32x4*)(gtp + 128 * bj) * acc[ai][bj][m][0], xo1 = xr[m][bj][1] + *(const LAS f32x4*)(gtp + 128 * bj + 4) * acc[ai][bj][m][1];
;                     *(f32x4*)(xout + off + 128 * bj) = xo0; *(f32x4*)(xout + off + 128 * bj + 4) = xo1;
.LBB0_363:
	s_andn2_b64 vcc, exec, s[54:55]
	s_cbranch_vccnz .LBB0_365
	v_pk_fma_f32 v[30:31], v[22:23], v[62:63], v[94:95]
	v_pk_fma_f32 v[26:27], v[14:15], v[58:59], v[90:91]
	ds_write_b128 v208, v[28:31]
	ds_write_b128 v208, v[24:27] offset:16
	ds_read_b128 v[216:219], v210
	ds_read_b128 v[220:223], v210 offset:1152
	s_waitcnt lgkmcnt(0)
	global_store_dwordx4 v40, v[216:219], s[6:7] offset:512
	global_store_dwordx4 v40, v[220:223], s[100:101] offset:512
.LBB0_365:
	s_waitcnt lgkmcnt(0)
	v_lshlrev_b64 v[12:13], 10, v[128:129]
	v_lshl_add_u64 v[14:15], v[12:13], 0, v[224:225]
	s_waitcnt vmcnt(10)
	v_pk_fma_f32 v[18:19], v[18:19], v[86:87], v[82:83]
	v_pk_fma_f32 v[16:17], v[16:17], v[84:85], v[80:81]
	v_pk_fma_f32 v[22:23], v[10:11], v[78:79], v[74:75]
	v_pk_fma_f32 v[20:21], v[8:9], v[76:77], v[72:73]
	v_lshl_add_u64 v[24:25], v[14:15], 2, s[6:7]
	v_lshl_add_u32 v24, v14, 2, v246
	s_mov_b64 s[54:55], -1
	s_and_b64 vcc, exec, s[46:47]
	s_waitcnt vmcnt(8)
	v_pk_fma_f32 v[12:13], v[4:5], v[60:61], v[68:69]
	v_pk_fma_f32 v[8:9], v[0:1], v[56:57], v[64:65]
	ds_write_b128 v208, v[16:19]
	ds_write_b128 v208, v[20:23] offset:16
	ds_read_b128 v[216:219], v210
	ds_read_b128 v[220:223], v210 offset:1152
	s_waitcnt lgkmcnt(0)
	global_store_dwordx4 v24, v[216:219], s[6:7]
	global_store_dwordx4 v24, v[220:223], s[100:101]
	s_cbranch_vccz .LBB0_372
	s_andn2_b64 vcc, exec, s[54:55]
	s_cbranch_vccz .LBB0_375

; #define LAS __attribute__((address_space(3)))
; __device__ __forceinline__ unsigned cvt_pk_bf16(float lo, float hi) { const cvt_f32x2_t v = {lo, hi}; const cvt_bf16x2_t b = __builtin_convertvector(v, cvt_bf16x2_t); return __builtin_bit_cast(unsigned, b); }
; __device__ __forceinline__ float sq4(f32x4 v) { return (v[0] * v[0] + v[1] * v[1]) + (v[2] * v[2] + v[3] * v[3]); }
;     __device__ __forceinline__ void operator()(const f32x4 (&acc)[2][2][4][2], const Unit& u, int wr, int wc, int fr, int fq) const {
;     ...
;                 for (int bj = 0; bj < 2; ++bj) {
;                     const f32x4 xo0 = xr[m][bj][0] + *(const LAS f32x4*)(gtp + 128 * bj) * acc[ai][bj][m][0], xo1 = xr[m][bj][1] + *(const LAS f32x4*)(gtp + 128 * bj + 4) * acc[ai][bj][m][1];
;                     *(f32x4*)(xout + off + 128 * bj) = xo0; *(f32x4*)(xout + off + 128 * bj + 4) = xo1;
;                     if (gmn) { ss += sq4(xo0) + sq4(xo1); const f32x4 a = xo0 * *(const LAS f32x4*)(gmp + 128 * bj), c = xo1 * *(const LAS f32x4*)(gmp + 128 * bj + 4);
;                         u32x4 w; w.x = cvt_pk_bf16(a[0], a[1]); w.y = cvt_pk_bf16(a[2], a[3]); w.z = cvt_pk_bf16(c[0], c[1]); w.w = cvt_pk_bf16(c[2], c[3]); *(u32x4*)(AX + off + 128 * bj) = w; }
;                 }
;                 if (gmn) { ss += __shfl_xor(ss, 16); ss += __shfl_xor(ss, 32); if (fq == 0) statx[(size_t)row * 16 + u.pn * 4 + wc] = ss; }
.LBB0_372:
	v_mul_f32_e32 v0, v17, v17
	v_mul_f32_e32 v1, v19, v19
	ds_read_b128 v[26:29], v192
	ds_read_b128 v[30:33], v192 offset:16
	v_fmac_f32_e32 v0, v16, v16
	v_fmac_f32_e32 v1, v18, v18
	v_add_f32_e32 v0, v0, v1
	v_mul_f32_e32 v1, v21, v21
	v_mul_f32_e32 v4, v23, v23
	v_fmac_f32_e32 v1, v20, v20
	v_fmac_f32_e32 v4, v22, v22
	v_add_f32_e32 v1, v1, v4
	v_add_f32_e32 v34, v0, v1
	s_waitcnt lgkmcnt(1)
	v_pk_mul_f32 v[0:1], v[18:19], v[28:29]
	v_pk_mul_f32 v[4:5], v[16:17], v[26:27]
	s_waitcnt lgkmcnt(0)
	v_pk_mul_f32 v[10:11], v[22:23], v[32:33]
	v_pk_mul_f32 v[18:19], v[20:21], v[30:31]
	v_cvt_pk_bf16_f32 v16, v4, v5
	v_cvt_pk_bf16_f32 v17, v0, v1
	v_cvt_pk_bf16_f32 v18, v18, v19
	v_cvt_pk_bf16_f32 v19, v10, v11
	v_lshl_add_u64 v[0:1], v[14:15], 1, s[16:17]
	v_lshl_add_u64 v[0:1], v[204:205], 0, v[0:1]
	v_pk_fma_f32 v[14:15], v[6:7], v[62:63], v[70:71]
	ds_bpermute_b32 v16, v206, v16
	ds_bpermute_b32 v17, v206, v17
	ds_bpermute_b32 v18, v206, v18
	ds_bpermute_b32 v19, v206, v19
	s_waitcnt lgkmcnt(0)
	global_store_dwordx4 v[0:1], v[16:19], off
	v_pk_fma_f32 v[10:11], v[2:3], v[58:59], v[66:67]
	ds_write_b128 v208, v[12:15]
	ds_write_b128 v208, v[8:11] offset:16
	ds_read_b128 v[216:219], v210
	ds_read_b128 v[220:223], v210 offset:1152
	ds_read_b128 v[16:19], v192 offset:512
	s_waitcnt lgkmcnt(0)
	v_pk_mul_f32 v[4:5], v[14:15], v[18:19]
	v_pk_mul_f32 v[20:21], v[12:13], v[16:17]
	ds_read_b128 v[16:19], v192 offset:528
	s_waitcnt lgkmcnt(0)
	v_pk_mul_f32 v[22:23], v[10:11], v[18:19]
	v_pk_mul_f32 v[18:19], v[8:9], v[16:17]
	v_cvt_pk_bf16_f32 v16, v20, v21
	v_cvt_pk_bf16_f32 v17, v4, v5
	s_waitcnt lgkmcnt(0)
	global_store_dwordx4 v24, v[216:219], s[6:7] offset:512
	global_store_dwordx4 v24, v[220:223], s[100:101] offset:512
	v_cvt_pk_bf16_f32 v18, v18, v19
	v_cvt_pk_bf16_f32 v19, v22, v23
	ds_bpermute_b32 v16, v206, v16
	ds_bpermute_b32 v17, v206, v17
	ds_bpermute_b32 v18, v206, v18
	ds_bpermute_b32 v19, v206, v19
	s_waitcnt lgkmcnt(0)
	global_store_dwordx4 v[0:1], v[16:19], off offset:256
	v_mul_f32_e32 v0, v13, v13
	v_mul_f32_e32 v1, v15, v15
	v_fmac_f32_e32 v0, v12, v12
	v_fmac_f32_e32 v1, v14, v14
	v_add_f32_e32 v0, v0, v1
	v_mul_f32_e32 v1, v9, v9
	v_mul_f32_e32 v4, v11, v11
	v_fmac_f32_e32 v1, v8, v8
	v_fmac_f32_e32 v4, v10, v10
	v_add_f32_e32 v1, v1, v4
	v_and_b32_e32 v4, 64, v242
	v_add_f32_e32 v0, v0, v1
	v_xor_b32_e32 v1, 16, v242
	v_add_u32_e32 v4, 64, v4
	v_cmp_lt_i32_e32 vcc, v1, v4
	v_add_f32_e32 v0, v34, v0
	s_nop 0
	v_cndmask_b32_e32 v1, v242, v1, vcc
	v_lshlrev_b32_e32 v1, 2, v1
	ds_bpermute_b32 v1, v1, v0
	s_waitcnt lgkmcnt(0)
	v_add_f32_e32 v0, v0, v1
	v_xor_b32_e32 v1, 32, v242
	v_cmp_lt_i32_e32 vcc, v1, v4
	s_nop 1
	v_cndmask_b32_e32 v1, v242, v1, vcc
	v_lshlrev_b32_e32 v1, 2, v1
	ds_bpermute_b32 v1, v1, v0
	s_and_saveexec_b64 s[46:47], s[44:45]
	s_cbranch_execz .LBB0_374
	v_lshlrev_b64 v[4:5], 6, v[128:129]
	v_lshl_add_u64 v[4:5], s[20:21], 0, v[4:5]
	v_lshl_add_u64 v[4:5], s[76:77], 2, v[4:5]
	s_lshl_b32 s92, s91, 2
	v_lshl_add_u64 v[4:5], v[4:5], 0, s[92:93]
	s_waitcnt lgkmcnt(0)
	v_add_f32_e32 v0, v0, v1
	global_store_dword v[4:5], v0, off

; #define LAS __attribute__((address_space(3)))
;     __device__ __forceinline__ void operator()(const f32x4 (&acc)[2][2][4][2], const Unit& u, int wr, int wc, int fr, int fq) const {
;     ...
;                     const f32x4 xo0 = xr[m][bj][0] + *(const LAS f32x4*)(gtp + 128 * bj) * acc[ai][bj][m][0], xo1 = xr[m][bj][1] + *(const LAS f32x4*)(gtp + 128 * bj + 4) * acc[ai][bj][m][1];
;                     *(f32x4*)(xout + off + 128 * bj) = xo0; *(f32x4*)(xout + off + 128 * bj + 4) = xo1;
.LBB0_375:
	v_pk_fma_f32 v[14:15], v[6:7], v[62:63], v[70:71]
	v_pk_fma_f32 v[10:11], v[2:3], v[58:59], v[66:67]
	ds_write_b128 v208, v[12:15]
	ds_write_b128 v208, v[8:11] offset:16
	ds_read_b128 v[216:219], v210
	ds_read_b128 v[220:223], v210 offset:1152
	s_waitcnt lgkmcnt(0)
	global_store_dwordx4 v24, v[216:219], s[6:7] offset:512
	global_store_dwordx4 v24, v[220:223], s[100:101] offset:512
	ds_read_b32 v216, v252
	ds_read_b32 v218, v252 offset:256
	ds_read_b32 v220, v252 offset:512
	ds_read_b32 v222, v252 offset:768
	v_mov_b32_e32 v217, v193
	v_mov_b32_e32 v219, v193
	v_mov_b32_e32 v221, v193
	v_mov_b32_e32 v223, v193
	s_waitcnt lgkmcnt(0)
	s_andn2_b64 vcc, exec, s[42:43]
	s_mov_b64 s[42:43], -1
	s_cbranch_vccnz .LBB0_308
